# plus: K-loop ds_read k0 fragments first and counted lgkmcnt ladder in front of MFMA blocks instead of lgkmcnt(0)
# speedup vs baseline: 1.0240x; 1.0116x over previous
.LBB0_270:
	s_ashr_i32 s11, s10, 31
	v_cmp_lt_i64_e32 vcc, s[14:15], v[152:153]
	s_lshl_b64 s[14:15], s[10:11], 19
	s_add_u32 s14, s68, s14
	s_addc_u32 s15, s69, s15
	s_and_b64 s[20:21], vcc, exec
	s_cselect_b32 s11, s15, s5
	s_cselect_b32 s43, s14, s4
	s_ashr_i32 s3, s2, 31
	s_lshl_b64 s[20:21], s[2:3], 19
	s_add_u32 s22, s25, s20
	s_addc_u32 s23, s36, s21
	s_and_b64 s[20:21], vcc, exec
	s_cselect_b32 s3, s23, s9
	s_cselect_b32 s73, s22, s8
	s_add_u32 s4, s4, 0x40080
	s_addc_u32 s5, s5, 0
	s_add_u32 s74, s8, 0x100
	v_mov_b32_e32 v0, 0
	s_addc_u32 s75, s9, 0
	s_mov_b32 s78, -2
	s_waitcnt lgkmcnt(0)
	s_add_u32 s8, s4, 0xfffc0080
	s_addc_u32 s9, s5, -1
	s_add_i32 s79, 0, 0x10000
	v_add_u32_e32 v142, s79, v159
	ds_read_b128 v[138:141], v142
	ds_read_b128 v[162:165], v142 offset:1024
	ds_read_b128 v[166:169], v142 offset:2048
	ds_read_b128 v[170:173], v142 offset:3072
	s_cmp_eq_u32 s78, 12
	s_cselect_b32 s21, s11, s9
	s_cselect_b32 s20, s43, s8
	s_cselect_b32 s9, s3, s75
	s_cselect_b32 s8, s73, s74
	v_lshl_add_u64 v[142:143], s[4:5], 0, v[134:135]
	s_add_i32 m0, s44, 0xc000
	ds_read_b128 v[188:191], v161
	ds_read_b128 v[196:199], v161 offset:2048
	ds_read_b128 v[204:207], v161 offset:4096
	ds_read_b128 v[212:215], v161 offset:6144
	ds_read_b128 v[192:195], v161 offset:1024
	ds_read_b128 v[200:203], v161 offset:3072
	ds_read_b128 v[208:211], v161 offset:5120
	ds_read_b128 v[216:219], v161 offset:7168
	global_load_lds_dwordx4 v[142:143], off
	v_lshl_add_u64 v[142:143], s[4:5], 0, v[136:137]
	s_add_i32 m0, s44, 0xe000
	s_nop 0
	global_load_lds_dwordx4 v[142:143], off
	s_waitcnt lgkmcnt(8)
	s_barrier
	s_setprio 1
	s_waitcnt lgkmcnt(7)
	v_mfma_f32_16x16x32_bf16 v[124:127], v[138:141], v[188:191], 0
	v_mfma_f32_16x16x32_bf16 v[120:123], v[166:169], v[188:191], 0
	s_waitcnt lgkmcnt(6)
	v_mfma_f32_16x16x32_bf16 v[108:111], v[138:141], v[196:199], 0
	v_mfma_f32_16x16x32_bf16 v[104:107], v[166:169], v[196:199], 0
	s_waitcnt lgkmcnt(5)
	v_mfma_f32_16x16x32_bf16 v[92:95], v[138:141], v[204:207], 0
	v_mfma_f32_16x16x32_bf16 v[88:91], v[166:169], v[204:207], 0
	s_waitcnt lgkmcnt(4)
	v_mfma_f32_16x16x32_bf16 v[76:79], v[138:141], v[212:215], 0
	v_mfma_f32_16x16x32_bf16 v[72:75], v[166:169], v[212:215], 0
	s_waitcnt lgkmcnt(3)
	v_mfma_f32_16x16x32_bf16 v[124:127], v[162:165], v[192:195], v[124:127]
	v_mfma_f32_16x16x32_bf16 v[120:123], v[170:173], v[192:195], v[120:123]
	s_waitcnt lgkmcnt(2)
	v_mfma_f32_16x16x32_bf16 v[108:111], v[162:165], v[200:203], v[108:111]
	v_mfma_f32_16x16x32_bf16 v[104:107], v[170:173], v[200:203], v[104:107]
	s_waitcnt lgkmcnt(1)
	v_mfma_f32_16x16x32_bf16 v[92:95], v[162:165], v[208:211], v[92:95]
	v_mfma_f32_16x16x32_bf16 v[88:91], v[170:173], v[208:211], v[88:91]
	s_waitcnt lgkmcnt(0)
	v_mfma_f32_16x16x32_bf16 v[76:79], v[162:165], v[216:219], v[76:79]
	v_mfma_f32_16x16x32_bf16 v[72:75], v[170:173], v[216:219], v[72:75]
	s_setprio 0
	s_barrier
	s_add_i32 s84, 0, 0x14000
	v_add_u32_e32 v142, s84, v159
	s_add_i32 s79, s79, s37
	ds_read_b128 v[220:223], v142
	ds_read_b128 v[224:227], v142 offset:1024
	ds_read_b128 v[228:231], v142 offset:2048
	ds_read_b128 v[232:235], v142 offset:3072
	v_lshl_add_u64 v[142:143], s[8:9], 0, v[148:149]
	s_mov_b32 m0, s79
	v_lshl_add_u64 v[174:175], s[8:9], 0, v[128:129]
	global_load_lds_dwordx4 v[142:143], off
	s_add_i32 m0, s79, 0x2000
	s_nop 0
	global_load_lds_dwordx4 v[174:175], off
	s_barrier
	s_setprio 1
	s_waitcnt lgkmcnt(3)
	v_mfma_f32_16x16x32_bf16 v[116:119], v[220:223], v[188:191], 0
	s_waitcnt lgkmcnt(1)
	v_mfma_f32_16x16x32_bf16 v[112:115], v[228:231], v[188:191], 0
	v_mfma_f32_16x16x32_bf16 v[100:103], v[220:223], v[196:199], 0
	v_mfma_f32_16x16x32_bf16 v[96:99], v[228:231], v[196:199], 0
	v_mfma_f32_16x16x32_bf16 v[84:87], v[220:223], v[204:207], 0
	v_mfma_f32_16x16x32_bf16 v[80:83], v[228:231], v[204:207], 0
	v_mfma_f32_16x16x32_bf16 v[68:71], v[220:223], v[212:215], 0
	v_mfma_f32_16x16x32_bf16 v[64:67], v[228:231], v[212:215], 0
	v_mfma_f32_16x16x32_bf16 v[116:119], v[224:227], v[192:195], v[116:119]
	s_waitcnt lgkmcnt(0)
	v_mfma_f32_16x16x32_bf16 v[112:115], v[232:235], v[192:195], v[112:115]
	v_mfma_f32_16x16x32_bf16 v[100:103], v[224:227], v[200:203], v[100:103]
	v_mfma_f32_16x16x32_bf16 v[96:99], v[232:235], v[200:203], v[96:99]
	v_mfma_f32_16x16x32_bf16 v[84:87], v[224:227], v[208:211], v[84:87]
	v_mfma_f32_16x16x32_bf16 v[80:83], v[232:235], v[208:211], v[80:83]
	v_mfma_f32_16x16x32_bf16 v[68:71], v[224:227], v[216:219], v[68:71]
	v_mfma_f32_16x16x32_bf16 v[64:67], v[232:235], v[216:219], v[64:67]
	s_setprio 0
	s_mov_b32 m0, s44
	v_lshl_add_u64 v[236:237], s[20:21], 0, v[132:133]
	s_barrier
	ds_read_b128 v[188:191], v161 offset:16384
	ds_read_b128 v[196:199], v161 offset:18432
	ds_read_b128 v[204:207], v161 offset:20480
	ds_read_b128 v[212:215], v161 offset:22528
	ds_read_b128 v[192:195], v161 offset:17408
	ds_read_b128 v[200:203], v161 offset:19456
	ds_read_b128 v[208:211], v161 offset:21504
	ds_read_b128 v[216:219], v161 offset:23552
	global_load_lds_dwordx4 v[236:237], off
	v_lshl_add_u64 v[238:239], s[20:21], 0, v[130:131]
	s_mov_b32 m0, s45
	s_nop 0
	global_load_lds_dwordx4 v[238:239], off
	s_barrier
	s_setprio 1
	s_waitcnt lgkmcnt(7)
	v_mfma_f32_16x16x32_bf16 v[60:63], v[138:141], v[188:191], 0
	v_mfma_f32_16x16x32_bf16 v[56:59], v[166:169], v[188:191], 0
	s_waitcnt lgkmcnt(6)
	v_mfma_f32_16x16x32_bf16 v[44:47], v[138:141], v[196:199], 0
	v_mfma_f32_16x16x32_bf16 v[40:43], v[166:169], v[196:199], 0
	s_waitcnt lgkmcnt(5)
	v_mfma_f32_16x16x32_bf16 v[28:31], v[138:141], v[204:207], 0
	v_mfma_f32_16x16x32_bf16 v[24:27], v[166:169], v[204:207], 0
	s_waitcnt lgkmcnt(4)
	v_mfma_f32_16x16x32_bf16 v[12:15], v[138:141], v[212:215], 0
	v_mfma_f32_16x16x32_bf16 v[8:11], v[166:169], v[212:215], 0
	s_waitcnt lgkmcnt(3)
	v_mfma_f32_16x16x32_bf16 v[60:63], v[162:165], v[192:195], v[60:63]
	v_mfma_f32_16x16x32_bf16 v[56:59], v[170:173], v[192:195], v[56:59]
	s_waitcnt lgkmcnt(2)
	v_mfma_f32_16x16x32_bf16 v[44:47], v[162:165], v[200:203], v[44:47]
	v_mfma_f32_16x16x32_bf16 v[40:43], v[170:173], v[200:203], v[40:43]
	s_waitcnt lgkmcnt(1)
	v_mfma_f32_16x16x32_bf16 v[28:31], v[162:165], v[208:211], v[28:31]
	v_mfma_f32_16x16x32_bf16 v[24:27], v[170:173], v[208:211], v[24:27]
	s_waitcnt lgkmcnt(0)
	v_mfma_f32_16x16x32_bf16 v[12:15], v[162:165], v[216:219], v[12:15]
	v_mfma_f32_16x16x32_bf16 v[8:11], v[170:173], v[216:219], v[8:11]
	s_setprio 0
	s_barrier
	s_add_u32 s80, s8, 0x40000
	s_addc_u32 s81, s9, 0
	s_add_i32 s79, s84, s37
	v_lshl_add_u64 v[138:139], s[80:81], 0, v[148:149]
	s_mov_b32 m0, s79
	s_nop 0
	global_load_lds_dwordx4 v[138:139], off
	v_lshl_add_u64 v[138:139], s[80:81], 0, v[128:129]
	s_add_i32 m0, s79, 0x2000
	s_nop 0
	global_load_lds_dwordx4 v[138:139], off
	s_waitcnt vmcnt(6)
	s_barrier
	s_setprio 1
	v_mfma_f32_16x16x32_bf16 v[52:55], v[220:223], v[188:191], 0
	v_mfma_f32_16x16x32_bf16 v[48:51], v[228:231], v[188:191], 0
	v_mfma_f32_16x16x32_bf16 v[36:39], v[220:223], v[196:199], 0
	v_mfma_f32_16x16x32_bf16 v[32:35], v[228:231], v[196:199], 0
	v_mfma_f32_16x16x32_bf16 v[20:23], v[220:223], v[204:207], 0
	v_mfma_f32_16x16x32_bf16 v[16:19], v[228:231], v[204:207], 0
	v_mfma_f32_16x16x32_bf16 v[4:7], v[220:223], v[212:215], 0
	v_mfma_f32_16x16x32_bf16 v[0:3], v[228:231], v[212:215], 0
	v_mfma_f32_16x16x32_bf16 v[52:55], v[224:227], v[192:195], v[52:55]
	v_mfma_f32_16x16x32_bf16 v[48:51], v[232:235], v[192:195], v[48:51]
	v_mfma_f32_16x16x32_bf16 v[36:39], v[224:227], v[200:203], v[36:39]
	v_mfma_f32_16x16x32_bf16 v[32:35], v[232:235], v[200:203], v[32:35]
	v_mfma_f32_16x16x32_bf16 v[20:23], v[224:227], v[208:211], v[20:23]
	v_mfma_f32_16x16x32_bf16 v[16:19], v[232:235], v[208:211], v[16:19]
	v_mfma_f32_16x16x32_bf16 v[4:7], v[224:227], v[216:219], v[4:7]
	v_mfma_f32_16x16x32_bf16 v[0:3], v[232:235], v[216:219], v[0:3]
	s_setprio 0
	s_add_i32 s79, 0, 0x18000
	v_add_u32_e32 v170, s79, v159
	s_barrier
	ds_read_b128 v[138:141], v170
	ds_read_b128 v[162:165], v170 offset:1024
	ds_read_b128 v[166:169], v170 offset:2048
	ds_read_b128 v[170:173], v170 offset:3072
	s_add_u32 s20, s20, 0x40000
	s_addc_u32 s21, s21, 0
	s_mov_b32 m0, s46
	v_lshl_add_u64 v[220:221], s[20:21], 0, v[132:133]
	ds_read_b128 v[188:191], v161 offset:32768
	ds_read_b128 v[196:199], v161 offset:34816
	ds_read_b128 v[204:207], v161 offset:36864
	ds_read_b128 v[212:215], v161 offset:38912
	ds_read_b128 v[192:195], v161 offset:33792
	ds_read_b128 v[200:203], v161 offset:35840
	ds_read_b128 v[208:211], v161 offset:37888
	ds_read_b128 v[216:219], v161 offset:39936
	global_load_lds_dwordx4 v[220:221], off
	v_lshl_add_u64 v[220:221], s[20:21], 0, v[130:131]
	s_mov_b32 m0, s47
	s_nop 0
	global_load_lds_dwordx4 v[220:221], off
	s_waitcnt lgkmcnt(8)
	s_barrier
	s_setprio 1
	s_waitcnt lgkmcnt(7)
	v_mfma_f32_16x16x32_bf16 v[124:127], v[138:141], v[188:191], v[124:127]
	v_mfma_f32_16x16x32_bf16 v[120:123], v[166:169], v[188:191], v[120:123]
	s_waitcnt lgkmcnt(6)
	v_mfma_f32_16x16x32_bf16 v[108:111], v[138:141], v[196:199], v[108:111]
	v_mfma_f32_16x16x32_bf16 v[104:107], v[166:169], v[196:199], v[104:107]
	s_waitcnt lgkmcnt(5)
	v_mfma_f32_16x16x32_bf16 v[92:95], v[138:141], v[204:207], v[92:95]
	v_mfma_f32_16x16x32_bf16 v[88:91], v[166:169], v[204:207], v[88:91]
	s_waitcnt lgkmcnt(4)
	v_mfma_f32_16x16x32_bf16 v[76:79], v[138:141], v[212:215], v[76:79]
	v_mfma_f32_16x16x32_bf16 v[72:75], v[166:169], v[212:215], v[72:75]
	s_waitcnt lgkmcnt(3)
	v_mfma_f32_16x16x32_bf16 v[124:127], v[162:165], v[192:195], v[124:127]
	v_mfma_f32_16x16x32_bf16 v[120:123], v[170:173], v[192:195], v[120:123]
	s_waitcnt lgkmcnt(2)
	v_mfma_f32_16x16x32_bf16 v[108:111], v[162:165], v[200:203], v[108:111]
	v_mfma_f32_16x16x32_bf16 v[104:107], v[170:173], v[200:203], v[104:107]
	s_waitcnt lgkmcnt(1)
	v_mfma_f32_16x16x32_bf16 v[92:95], v[162:165], v[208:211], v[92:95]
	v_mfma_f32_16x16x32_bf16 v[88:91], v[170:173], v[208:211], v[88:91]
	s_waitcnt lgkmcnt(0)
	v_mfma_f32_16x16x32_bf16 v[76:79], v[162:165], v[216:219], v[76:79]
	v_mfma_f32_16x16x32_bf16 v[72:75], v[170:173], v[216:219], v[72:75]
	s_setprio 0
	s_barrier
	s_add_i32 s20, 0, 0x1c000
	s_add_i32 s21, s79, s37
	v_add_u32_e32 v232, s20, v159
	v_lshl_add_u64 v[142:143], v[142:143], 0, s[28:29]
	s_mov_b32 m0, s21
	ds_read_b128 v[220:223], v232
	ds_read_b128 v[224:227], v232 offset:1024
	ds_read_b128 v[228:231], v232 offset:2048
	ds_read_b128 v[232:235], v232 offset:3072
	global_load_lds_dwordx4 v[142:143], off
	v_lshl_add_u64 v[142:143], v[174:175], 0, s[28:29]
	s_add_i32 m0, s21, 0x2000
	s_nop 0
	global_load_lds_dwordx4 v[142:143], off
	s_barrier
	s_setprio 1
	s_waitcnt lgkmcnt(3)
	v_mfma_f32_16x16x32_bf16 v[116:119], v[220:223], v[188:191], v[116:119]
	s_waitcnt lgkmcnt(1)
	v_mfma_f32_16x16x32_bf16 v[112:115], v[228:231], v[188:191], v[112:115]
	v_mfma_f32_16x16x32_bf16 v[100:103], v[220:223], v[196:199], v[100:103]
	v_mfma_f32_16x16x32_bf16 v[96:99], v[228:231], v[196:199], v[96:99]
	v_mfma_f32_16x16x32_bf16 v[84:87], v[220:223], v[204:207], v[84:87]
	v_mfma_f32_16x16x32_bf16 v[80:83], v[228:231], v[204:207], v[80:83]
	v_mfma_f32_16x16x32_bf16 v[68:71], v[220:223], v[212:215], v[68:71]
	v_mfma_f32_16x16x32_bf16 v[64:67], v[228:231], v[212:215], v[64:67]
	v_mfma_f32_16x16x32_bf16 v[116:119], v[224:227], v[192:195], v[116:119]
	s_waitcnt lgkmcnt(0)
	v_mfma_f32_16x16x32_bf16 v[112:115], v[232:235], v[192:195], v[112:115]
	v_mfma_f32_16x16x32_bf16 v[100:103], v[224:227], v[200:203], v[100:103]
	v_mfma_f32_16x16x32_bf16 v[96:99], v[232:235], v[200:203], v[96:99]
	v_mfma_f32_16x16x32_bf16 v[84:87], v[224:227], v[208:211], v[84:87]
	v_mfma_f32_16x16x32_bf16 v[80:83], v[232:235], v[208:211], v[80:83]
	v_mfma_f32_16x16x32_bf16 v[68:71], v[224:227], v[216:219], v[68:71]
	v_mfma_f32_16x16x32_bf16 v[64:67], v[232:235], v[216:219], v[64:67]
	s_setprio 0
	s_mov_b32 m0, s51
	v_lshl_add_u64 v[142:143], v[236:237], 0, s[28:29]
	s_barrier
	ds_read_b128 v[188:191], v161 offset:49152
	ds_read_b128 v[196:199], v161 offset:51200
	ds_read_b128 v[204:207], v161 offset:53248
	ds_read_b128 v[212:215], v161 offset:55296
	ds_read_b128 v[192:195], v161 offset:50176
	ds_read_b128 v[200:203], v161 offset:52224
	ds_read_b128 v[208:211], v161 offset:54272
	ds_read_b128 v[216:219], v161 offset:56320
	global_load_lds_dwordx4 v[142:143], off
	v_lshl_add_u64 v[142:143], v[238:239], 0, s[28:29]
	s_mov_b32 m0, s64
	s_nop 0
	global_load_lds_dwordx4 v[142:143], off
	s_barrier
	s_setprio 1
	s_waitcnt lgkmcnt(7)
	v_mfma_f32_16x16x32_bf16 v[60:63], v[138:141], v[188:191], v[60:63]
	v_mfma_f32_16x16x32_bf16 v[56:59], v[166:169], v[188:191], v[56:59]
	s_waitcnt lgkmcnt(6)
	v_mfma_f32_16x16x32_bf16 v[44:47], v[138:141], v[196:199], v[44:47]
	v_mfma_f32_16x16x32_bf16 v[40:43], v[166:169], v[196:199], v[40:43]
	s_waitcnt lgkmcnt(5)
	v_mfma_f32_16x16x32_bf16 v[28:31], v[138:141], v[204:207], v[28:31]
	v_mfma_f32_16x16x32_bf16 v[24:27], v[166:169], v[204:207], v[24:27]
	s_waitcnt lgkmcnt(4)
	v_mfma_f32_16x16x32_bf16 v[12:15], v[138:141], v[212:215], v[12:15]
	v_mfma_f32_16x16x32_bf16 v[8:11], v[166:169], v[212:215], v[8:11]
	s_waitcnt lgkmcnt(3)
	v_mfma_f32_16x16x32_bf16 v[60:63], v[162:165], v[192:195], v[60:63]
	v_mfma_f32_16x16x32_bf16 v[56:59], v[170:173], v[192:195], v[56:59]
	s_waitcnt lgkmcnt(2)
	v_mfma_f32_16x16x32_bf16 v[44:47], v[162:165], v[200:203], v[44:47]
	v_mfma_f32_16x16x32_bf16 v[40:43], v[170:173], v[200:203], v[40:43]
	s_waitcnt lgkmcnt(1)
	v_mfma_f32_16x16x32_bf16 v[28:31], v[162:165], v[208:211], v[28:31]
	v_mfma_f32_16x16x32_bf16 v[24:27], v[170:173], v[208:211], v[24:27]
	s_waitcnt lgkmcnt(0)
	v_mfma_f32_16x16x32_bf16 v[12:15], v[162:165], v[216:219], v[12:15]
	v_mfma_f32_16x16x32_bf16 v[8:11], v[170:173], v[216:219], v[8:11]
	s_setprio 0
	s_barrier
	s_add_u32 s8, s8, 0x40080
	s_addc_u32 s9, s9, 0
	s_add_i32 s20, s20, s37
	v_lshl_add_u64 v[138:139], s[8:9], 0, v[148:149]
	s_mov_b32 m0, s20
	s_nop 0
	global_load_lds_dwordx4 v[138:139], off
	v_lshl_add_u64 v[138:139], s[8:9], 0, v[128:129]
	s_add_i32 m0, s20, 0x2000
	s_nop 0
	global_load_lds_dwordx4 v[138:139], off
	s_waitcnt vmcnt(6)
	s_barrier
	s_setprio 1
	v_mfma_f32_16x16x32_bf16 v[52:55], v[220:223], v[188:191], v[52:55]
	v_mfma_f32_16x16x32_bf16 v[48:51], v[228:231], v[188:191], v[48:51]
	v_mfma_f32_16x16x32_bf16 v[36:39], v[220:223], v[196:199], v[36:39]
	v_mfma_f32_16x16x32_bf16 v[32:35], v[228:231], v[196:199], v[32:35]
	v_mfma_f32_16x16x32_bf16 v[20:23], v[220:223], v[204:207], v[20:23]
	v_mfma_f32_16x16x32_bf16 v[16:19], v[228:231], v[204:207], v[16:19]
	v_mfma_f32_16x16x32_bf16 v[4:7], v[220:223], v[212:215], v[4:7]
	v_mfma_f32_16x16x32_bf16 v[0:3], v[228:231], v[212:215], v[0:3]
	v_mfma_f32_16x16x32_bf16 v[52:55], v[224:227], v[192:195], v[52:55]
	v_mfma_f32_16x16x32_bf16 v[48:51], v[232:235], v[192:195], v[48:51]
	v_mfma_f32_16x16x32_bf16 v[36:39], v[224:227], v[200:203], v[36:39]
	v_mfma_f32_16x16x32_bf16 v[32:35], v[232:235], v[200:203], v[32:35]
	v_mfma_f32_16x16x32_bf16 v[20:23], v[224:227], v[208:211], v[20:23]
	v_mfma_f32_16x16x32_bf16 v[16:19], v[232:235], v[208:211], v[16:19]
	v_mfma_f32_16x16x32_bf16 v[4:7], v[224:227], v[216:219], v[4:7]
	v_mfma_f32_16x16x32_bf16 v[0:3], v[232:235], v[216:219], v[0:3]
	s_setprio 0
	s_add_i32 s78, s78, 2
	s_add_u32 s4, s4, 0x100
	s_addc_u32 s5, s5, 0
	s_add_u32 s74, s74, 0x100
	s_addc_u32 s75, s75, 0
	s_cmp_gt_u32 s78, 13
	s_barrier
	s_cbranch_scc1 .Lpeel_after_g0
.LBB0_271:
	s_add_u32 s8, s4, 0xfffc0080
	s_addc_u32 s9, s5, -1
	s_add_i32 s79, 0, 0x10000
	v_add_u32_e32 v142, s79, v159
	ds_read_b128 v[138:141], v142
	ds_read_b128 v[162:165], v142 offset:1024
	ds_read_b128 v[166:169], v142 offset:2048
	ds_read_b128 v[170:173], v142 offset:3072
	s_cmp_eq_u32 s78, 12
	s_cselect_b32 s21, s11, s9
	s_cselect_b32 s20, s43, s8
	s_cselect_b32 s9, s3, s75
	s_cselect_b32 s8, s73, s74
	v_lshl_add_u64 v[142:143], s[4:5], 0, v[134:135]
	s_add_i32 m0, s44, 0xc000
	ds_read_b128 v[188:191], v161
	ds_read_b128 v[196:199], v161 offset:2048
	ds_read_b128 v[204:207], v161 offset:4096
	ds_read_b128 v[212:215], v161 offset:6144
	ds_read_b128 v[192:195], v161 offset:1024
	ds_read_b128 v[200:203], v161 offset:3072
	ds_read_b128 v[208:211], v161 offset:5120
	ds_read_b128 v[216:219], v161 offset:7168
	global_load_lds_dwordx4 v[142:143], off
	v_lshl_add_u64 v[142:143], s[4:5], 0, v[136:137]
	s_add_i32 m0, s44, 0xe000
	s_nop 0
	global_load_lds_dwordx4 v[142:143], off
	s_waitcnt lgkmcnt(8)
	s_barrier
	s_setprio 1
	s_waitcnt lgkmcnt(7)
	v_mfma_f32_16x16x32_bf16 v[124:127], v[138:141], v[188:191], v[124:127]
	v_mfma_f32_16x16x32_bf16 v[120:123], v[166:169], v[188:191], v[120:123]
	s_waitcnt lgkmcnt(6)
	v_mfma_f32_16x16x32_bf16 v[108:111], v[138:141], v[196:199], v[108:111]
	v_mfma_f32_16x16x32_bf16 v[104:107], v[166:169], v[196:199], v[104:107]
	s_waitcnt lgkmcnt(5)
	v_mfma_f32_16x16x32_bf16 v[92:95], v[138:141], v[204:207], v[92:95]
	v_mfma_f32_16x16x32_bf16 v[88:91], v[166:169], v[204:207], v[88:91]
	s_waitcnt lgkmcnt(4)
	v_mfma_f32_16x16x32_bf16 v[76:79], v[138:141], v[212:215], v[76:79]
	v_mfma_f32_16x16x32_bf16 v[72:75], v[166:169], v[212:215], v[72:75]
	s_waitcnt lgkmcnt(3)
	v_mfma_f32_16x16x32_bf16 v[124:127], v[162:165], v[192:195], v[124:127]
	v_mfma_f32_16x16x32_bf16 v[120:123], v[170:173], v[192:195], v[120:123]
	s_waitcnt lgkmcnt(2)
	v_mfma_f32_16x16x32_bf16 v[108:111], v[162:165], v[200:203], v[108:111]
	v_mfma_f32_16x16x32_bf16 v[104:107], v[170:173], v[200:203], v[104:107]
	s_waitcnt lgkmcnt(1)
	v_mfma_f32_16x16x32_bf16 v[92:95], v[162:165], v[208:211], v[92:95]
	v_mfma_f32_16x16x32_bf16 v[88:91], v[170:173], v[208:211], v[88:91]
	s_waitcnt lgkmcnt(0)
	v_mfma_f32_16x16x32_bf16 v[76:79], v[162:165], v[216:219], v[76:79]
	v_mfma_f32_16x16x32_bf16 v[72:75], v[170:173], v[216:219], v[72:75]
	s_setprio 0
	s_barrier
	s_add_i32 s84, 0, 0x14000
	v_add_u32_e32 v142, s84, v159
	s_add_i32 s79, s79, s37
	ds_read_b128 v[220:223], v142
	ds_read_b128 v[224:227], v142 offset:1024
	ds_read_b128 v[228:231], v142 offset:2048
	ds_read_b128 v[232:235], v142 offset:3072
	v_lshl_add_u64 v[142:143], s[8:9], 0, v[148:149]
	s_mov_b32 m0, s79
	v_lshl_add_u64 v[174:175], s[8:9], 0, v[128:129]
	global_load_lds_dwordx4 v[142:143], off
	s_add_i32 m0, s79, 0x2000
	s_nop 0
	global_load_lds_dwordx4 v[174:175], off
	s_barrier
	s_setprio 1
	s_waitcnt lgkmcnt(3)
	v_mfma_f32_16x16x32_bf16 v[116:119], v[220:223], v[188:191], v[116:119]
	s_waitcnt lgkmcnt(1)
	v_mfma_f32_16x16x32_bf16 v[112:115], v[228:231], v[188:191], v[112:115]
	v_mfma_f32_16x16x32_bf16 v[100:103], v[220:223], v[196:199], v[100:103]
	v_mfma_f32_16x16x32_bf16 v[96:99], v[228:231], v[196:199], v[96:99]
	v_mfma_f32_16x16x32_bf16 v[84:87], v[220:223], v[204:207], v[84:87]
	v_mfma_f32_16x16x32_bf16 v[80:83], v[228:231], v[204:207], v[80:83]
	v_mfma_f32_16x16x32_bf16 v[68:71], v[220:223], v[212:215], v[68:71]
	v_mfma_f32_16x16x32_bf16 v[64:67], v[228:231], v[212:215], v[64:67]
	v_mfma_f32_16x16x32_bf16 v[116:119], v[224:227], v[192:195], v[116:119]
	s_waitcnt lgkmcnt(0)
	v_mfma_f32_16x16x32_bf16 v[112:115], v[232:235], v[192:195], v[112:115]
	v_mfma_f32_16x16x32_bf16 v[100:103], v[224:227], v[200:203], v[100:103]
	v_mfma_f32_16x16x32_bf16 v[96:99], v[232:235], v[200:203], v[96:99]
	v_mfma_f32_16x16x32_bf16 v[84:87], v[224:227], v[208:211], v[84:87]
	v_mfma_f32_16x16x32_bf16 v[80:83], v[232:235], v[208:211], v[80:83]
	v_mfma_f32_16x16x32_bf16 v[68:71], v[224:227], v[216:219], v[68:71]
	v_mfma_f32_16x16x32_bf16 v[64:67], v[232:235], v[216:219], v[64:67]
	s_setprio 0
	s_mov_b32 m0, s44
	v_lshl_add_u64 v[236:237], s[20:21], 0, v[132:133]
	s_barrier
	ds_read_b128 v[188:191], v161 offset:16384
	ds_read_b128 v[196:199], v161 offset:18432
	ds_read_b128 v[204:207], v161 offset:20480
	ds_read_b128 v[212:215], v161 offset:22528
	ds_read_b128 v[192:195], v161 offset:17408
	ds_read_b128 v[200:203], v161 offset:19456
	ds_read_b128 v[208:211], v161 offset:21504
	ds_read_b128 v[216:219], v161 offset:23552
	global_load_lds_dwordx4 v[236:237], off
	v_lshl_add_u64 v[238:239], s[20:21], 0, v[130:131]
	s_mov_b32 m0, s45
	s_nop 0
	global_load_lds_dwordx4 v[238:239], off
	s_barrier
	s_setprio 1
	s_waitcnt lgkmcnt(7)
	v_mfma_f32_16x16x32_bf16 v[60:63], v[138:141], v[188:191], v[60:63]
	v_mfma_f32_16x16x32_bf16 v[56:59], v[166:169], v[188:191], v[56:59]
	s_waitcnt lgkmcnt(6)
	v_mfma_f32_16x16x32_bf16 v[44:47], v[138:141], v[196:199], v[44:47]
	v_mfma_f32_16x16x32_bf16 v[40:43], v[166:169], v[196:199], v[40:43]
	s_waitcnt lgkmcnt(5)
	v_mfma_f32_16x16x32_bf16 v[28:31], v[138:141], v[204:207], v[28:31]
	v_mfma_f32_16x16x32_bf16 v[24:27], v[166:169], v[204:207], v[24:27]
	s_waitcnt lgkmcnt(4)
	v_mfma_f32_16x16x32_bf16 v[12:15], v[138:141], v[212:215], v[12:15]
	v_mfma_f32_16x16x32_bf16 v[8:11], v[166:169], v[212:215], v[8:11]
	s_waitcnt lgkmcnt(3)
	v_mfma_f32_16x16x32_bf16 v[60:63], v[162:165], v[192:195], v[60:63]
	v_mfma_f32_16x16x32_bf16 v[56:59], v[170:173], v[192:195], v[56:59]
	s_waitcnt lgkmcnt(2)
	v_mfma_f32_16x16x32_bf16 v[44:47], v[162:165], v[200:203], v[44:47]
	v_mfma_f32_16x16x32_bf16 v[40:43], v[170:173], v[200:203], v[40:43]
	s_waitcnt lgkmcnt(1)
	v_mfma_f32_16x16x32_bf16 v[28:31], v[162:165], v[208:211], v[28:31]
	v_mfma_f32_16x16x32_bf16 v[24:27], v[170:173], v[208:211], v[24:27]
	s_waitcnt lgkmcnt(0)
	v_mfma_f32_16x16x32_bf16 v[12:15], v[162:165], v[216:219], v[12:15]
	v_mfma_f32_16x16x32_bf16 v[8:11], v[170:173], v[216:219], v[8:11]
	s_setprio 0
	s_barrier
	s_add_u32 s80, s8, 0x40000
	s_addc_u32 s81, s9, 0
	s_add_i32 s79, s84, s37
	v_lshl_add_u64 v[138:139], s[80:81], 0, v[148:149]
	s_mov_b32 m0, s79
	s_nop 0
	global_load_lds_dwordx4 v[138:139], off
	v_lshl_add_u64 v[138:139], s[80:81], 0, v[128:129]
	s_add_i32 m0, s79, 0x2000
	s_nop 0
	global_load_lds_dwordx4 v[138:139], off
	s_waitcnt vmcnt(6)
	s_barrier
	s_setprio 1
	v_mfma_f32_16x16x32_bf16 v[52:55], v[220:223], v[188:191], v[52:55]
	v_mfma_f32_16x16x32_bf16 v[48:51], v[228:231], v[188:191], v[48:51]
	v_mfma_f32_16x16x32_bf16 v[36:39], v[220:223], v[196:199], v[36:39]
	v_mfma_f32_16x16x32_bf16 v[32:35], v[228:231], v[196:199], v[32:35]
	v_mfma_f32_16x16x32_bf16 v[20:23], v[220:223], v[204:207], v[20:23]
	v_mfma_f32_16x16x32_bf16 v[16:19], v[228:231], v[204:207], v[16:19]
	v_mfma_f32_16x16x32_bf16 v[4:7], v[220:223], v[212:215], v[4:7]
	v_mfma_f32_16x16x32_bf16 v[0:3], v[228:231], v[212:215], v[0:3]
	v_mfma_f32_16x16x32_bf16 v[52:55], v[224:227], v[192:195], v[52:55]
	v_mfma_f32_16x16x32_bf16 v[48:51], v[232:235], v[192:195], v[48:51]
	v_mfma_f32_16x16x32_bf16 v[36:39], v[224:227], v[200:203], v[36:39]
	v_mfma_f32_16x16x32_bf16 v[32:35], v[232:235], v[200:203], v[32:35]
	v_mfma_f32_16x16x32_bf16 v[20:23], v[224:227], v[208:211], v[20:23]
	v_mfma_f32_16x16x32_bf16 v[16:19], v[232:235], v[208:211], v[16:19]
	v_mfma_f32_16x16x32_bf16 v[4:7], v[224:227], v[216:219], v[4:7]
	v_mfma_f32_16x16x32_bf16 v[0:3], v[232:235], v[216:219], v[0:3]
	s_setprio 0
	s_add_i32 s79, 0, 0x18000
	v_add_u32_e32 v170, s79, v159
	s_barrier
	ds_read_b128 v[138:141], v170
	ds_read_b128 v[162:165], v170 offset:1024
	ds_read_b128 v[166:169], v170 offset:2048
	ds_read_b128 v[170:173], v170 offset:3072
	s_add_u32 s20, s20, 0x40000
	s_addc_u32 s21, s21, 0
	s_mov_b32 m0, s46
	v_lshl_add_u64 v[220:221], s[20:21], 0, v[132:133]
	ds_read_b128 v[188:191], v161 offset:32768
	ds_read_b128 v[196:199], v161 offset:34816
	ds_read_b128 v[204:207], v161 offset:36864
	ds_read_b128 v[212:215], v161 offset:38912
	ds_read_b128 v[192:195], v161 offset:33792
	ds_read_b128 v[200:203], v161 offset:35840
	ds_read_b128 v[208:211], v161 offset:37888
	ds_read_b128 v[216:219], v161 offset:39936
	global_load_lds_dwordx4 v[220:221], off
	v_lshl_add_u64 v[220:221], s[20:21], 0, v[130:131]
	s_mov_b32 m0, s47
	s_nop 0
	global_load_lds_dwordx4 v[220:221], off
	s_waitcnt lgkmcnt(8)
	s_barrier
	s_setprio 1
	s_waitcnt lgkmcnt(7)
	v_mfma_f32_16x16x32_bf16 v[124:127], v[138:141], v[188:191], v[124:127]
	v_mfma_f32_16x16x32_bf16 v[120:123], v[166:169], v[188:191], v[120:123]
	s_waitcnt lgkmcnt(6)
	v_mfma_f32_16x16x32_bf16 v[108:111], v[138:141], v[196:199], v[108:111]
	v_mfma_f32_16x16x32_bf16 v[104:107], v[166:169], v[196:199], v[104:107]
	s_waitcnt lgkmcnt(5)
	v_mfma_f32_16x16x32_bf16 v[92:95], v[138:141], v[204:207], v[92:95]
	v_mfma_f32_16x16x32_bf16 v[88:91], v[166:169], v[204:207], v[88:91]
	s_waitcnt lgkmcnt(4)
	v_mfma_f32_16x16x32_bf16 v[76:79], v[138:141], v[212:215], v[76:79]
	v_mfma_f32_16x16x32_bf16 v[72:75], v[166:169], v[212:215], v[72:75]
	s_waitcnt lgkmcnt(3)
	v_mfma_f32_16x16x32_bf16 v[124:127], v[162:165], v[192:195], v[124:127]
	v_mfma_f32_16x16x32_bf16 v[120:123], v[170:173], v[192:195], v[120:123]
	s_waitcnt lgkmcnt(2)
	v_mfma_f32_16x16x32_bf16 v[108:111], v[162:165], v[200:203], v[108:111]
	v_mfma_f32_16x16x32_bf16 v[104:107], v[170:173], v[200:203], v[104:107]
	s_waitcnt lgkmcnt(1)
	v_mfma_f32_16x16x32_bf16 v[92:95], v[162:165], v[208:211], v[92:95]
	v_mfma_f32_16x16x32_bf16 v[88:91], v[170:173], v[208:211], v[88:91]
	s_waitcnt lgkmcnt(0)
	v_mfma_f32_16x16x32_bf16 v[76:79], v[162:165], v[216:219], v[76:79]
	v_mfma_f32_16x16x32_bf16 v[72:75], v[170:173], v[216:219], v[72:75]
	s_setprio 0
	s_barrier
	s_add_i32 s20, 0, 0x1c000
	s_add_i32 s21, s79, s37
	v_add_u32_e32 v232, s20, v159
	v_lshl_add_u64 v[142:143], v[142:143], 0, s[28:29]
	s_mov_b32 m0, s21
	ds_read_b128 v[220:223], v232
	ds_read_b128 v[224:227], v232 offset:1024
	ds_read_b128 v[228:231], v232 offset:2048
	ds_read_b128 v[232:235], v232 offset:3072
	global_load_lds_dwordx4 v[142:143], off
	v_lshl_add_u64 v[142:143], v[174:175], 0, s[28:29]
	s_add_i32 m0, s21, 0x2000
	s_nop 0
	global_load_lds_dwordx4 v[142:143], off
	s_barrier
	s_setprio 1
	s_waitcnt lgkmcnt(3)
	v_mfma_f32_16x16x32_bf16 v[116:119], v[220:223], v[188:191], v[116:119]
	s_waitcnt lgkmcnt(1)
	v_mfma_f32_16x16x32_bf16 v[112:115], v[228:231], v[188:191], v[112:115]
	v_mfma_f32_16x16x32_bf16 v[100:103], v[220:223], v[196:199], v[100:103]
	v_mfma_f32_16x16x32_bf16 v[96:99], v[228:231], v[196:199], v[96:99]
	v_mfma_f32_16x16x32_bf16 v[84:87], v[220:223], v[204:207], v[84:87]
	v_mfma_f32_16x16x32_bf16 v[80:83], v[228:231], v[204:207], v[80:83]
	v_mfma_f32_16x16x32_bf16 v[68:71], v[220:223], v[212:215], v[68:71]
	v_mfma_f32_16x16x32_bf16 v[64:67], v[228:231], v[212:215], v[64:67]
	v_mfma_f32_16x16x32_bf16 v[116:119], v[224:227], v[192:195], v[116:119]
	s_waitcnt lgkmcnt(0)
	v_mfma_f32_16x16x32_bf16 v[112:115], v[232:235], v[192:195], v[112:115]
	v_mfma_f32_16x16x32_bf16 v[100:103], v[224:227], v[200:203], v[100:103]
	v_mfma_f32_16x16x32_bf16 v[96:99], v[232:235], v[200:203], v[96:99]
	v_mfma_f32_16x16x32_bf16 v[84:87], v[224:227], v[208:211], v[84:87]
	v_mfma_f32_16x16x32_bf16 v[80:83], v[232:235], v[208:211], v[80:83]
	v_mfma_f32_16x16x32_bf16 v[68:71], v[224:227], v[216:219], v[68:71]
	v_mfma_f32_16x16x32_bf16 v[64:67], v[232:235], v[216:219], v[64:67]
	s_setprio 0
	s_mov_b32 m0, s51
	v_lshl_add_u64 v[142:143], v[236:237], 0, s[28:29]
	s_barrier
	ds_read_b128 v[188:191], v161 offset:49152
	ds_read_b128 v[196:199], v161 offset:51200
	ds_read_b128 v[204:207], v161 offset:53248
	ds_read_b128 v[212:215], v161 offset:55296
	ds_read_b128 v[192:195], v161 offset:50176
	ds_read_b128 v[200:203], v161 offset:52224
	ds_read_b128 v[208:211], v161 offset:54272
	ds_read_b128 v[216:219], v161 offset:56320
	global_load_lds_dwordx4 v[142:143], off
	v_lshl_add_u64 v[142:143], v[238:239], 0, s[28:29]
	s_mov_b32 m0, s64
	s_nop 0
	global_load_lds_dwordx4 v[142:143], off
	s_barrier
	s_setprio 1
	s_waitcnt lgkmcnt(7)
	v_mfma_f32_16x16x32_bf16 v[60:63], v[138:141], v[188:191], v[60:63]
	v_mfma_f32_16x16x32_bf16 v[56:59], v[166:169], v[188:191], v[56:59]
	s_waitcnt lgkmcnt(6)
	v_mfma_f32_16x16x32_bf16 v[44:47], v[138:141], v[196:199], v[44:47]
	v_mfma_f32_16x16x32_bf16 v[40:43], v[166:169], v[196:199], v[40:43]
	s_waitcnt lgkmcnt(5)
	v_mfma_f32_16x16x32_bf16 v[28:31], v[138:141], v[204:207], v[28:31]
	v_mfma_f32_16x16x32_bf16 v[24:27], v[166:169], v[204:207], v[24:27]
	s_waitcnt lgkmcnt(4)
	v_mfma_f32_16x16x32_bf16 v[12:15], v[138:141], v[212:215], v[12:15]
	v_mfma_f32_16x16x32_bf16 v[8:11], v[166:169], v[212:215], v[8:11]
	s_waitcnt lgkmcnt(3)
	v_mfma_f32_16x16x32_bf16 v[60:63], v[162:165], v[192:195], v[60:63]
	v_mfma_f32_16x16x32_bf16 v[56:59], v[170:173], v[192:195], v[56:59]
	s_waitcnt lgkmcnt(2)
	v_mfma_f32_16x16x32_bf16 v[44:47], v[162:165], v[200:203], v[44:47]
	v_mfma_f32_16x16x32_bf16 v[40:43], v[170:173], v[200:203], v[40:43]
	s_waitcnt lgkmcnt(1)
	v_mfma_f32_16x16x32_bf16 v[28:31], v[162:165], v[208:211], v[28:31]
	v_mfma_f32_16x16x32_bf16 v[24:27], v[170:173], v[208:211], v[24:27]
	s_waitcnt lgkmcnt(0)
	v_mfma_f32_16x16x32_bf16 v[12:15], v[162:165], v[216:219], v[12:15]
	v_mfma_f32_16x16x32_bf16 v[8:11], v[170:173], v[216:219], v[8:11]
	s_setprio 0
	s_barrier
	s_add_u32 s8, s8, 0x40080
	s_addc_u32 s9, s9, 0
	s_add_i32 s20, s20, s37
	v_lshl_add_u64 v[138:139], s[8:9], 0, v[148:149]
	s_mov_b32 m0, s20
	s_nop 0
	global_load_lds_dwordx4 v[138:139], off
	v_lshl_add_u64 v[138:139], s[8:9], 0, v[128:129]
	s_add_i32 m0, s20, 0x2000
	s_nop 0
	global_load_lds_dwordx4 v[138:139], off
	s_waitcnt vmcnt(6)
	s_barrier
	s_setprio 1
	v_mfma_f32_16x16x32_bf16 v[52:55], v[220:223], v[188:191], v[52:55]
	v_mfma_f32_16x16x32_bf16 v[48:51], v[228:231], v[188:191], v[48:51]
	v_mfma_f32_16x16x32_bf16 v[36:39], v[220:223], v[196:199], v[36:39]
	v_mfma_f32_16x16x32_bf16 v[32:35], v[228:231], v[196:199], v[32:35]
	v_mfma_f32_16x16x32_bf16 v[20:23], v[220:223], v[204:207], v[20:23]
	v_mfma_f32_16x16x32_bf16 v[16:19], v[228:231], v[204:207], v[16:19]
	v_mfma_f32_16x16x32_bf16 v[4:7], v[220:223], v[212:215], v[4:7]
	v_mfma_f32_16x16x32_bf16 v[0:3], v[228:231], v[212:215], v[0:3]
	v_mfma_f32_16x16x32_bf16 v[52:55], v[224:227], v[192:195], v[52:55]
	v_mfma_f32_16x16x32_bf16 v[48:51], v[232:235], v[192:195], v[48:51]
	v_mfma_f32_16x16x32_bf16 v[36:39], v[224:227], v[200:203], v[36:39]
	v_mfma_f32_16x16x32_bf16 v[32:35], v[232:235], v[200:203], v[32:35]
	v_mfma_f32_16x16x32_bf16 v[20:23], v[224:227], v[208:211], v[20:23]
	v_mfma_f32_16x16x32_bf16 v[16:19], v[232:235], v[208:211], v[16:19]
	v_mfma_f32_16x16x32_bf16 v[4:7], v[224:227], v[216:219], v[4:7]
	v_mfma_f32_16x16x32_bf16 v[0:3], v[232:235], v[216:219], v[0:3]
	s_setprio 0
	s_add_i32 s78, s78, 2
	s_add_u32 s4, s4, 0x100
	s_addc_u32 s5, s5, 0
	s_add_u32 s74, s74, 0x100
	s_addc_u32 s75, s75, 0
	s_cmp_gt_u32 s78, 13
	s_barrier
	s_cbranch_scc0 .LBB0_271

.LBB0_489:
	s_add_u32 s0, s44, 0x80
	s_addc_u32 s1, s45, 0
	s_add_u32 vcc_lo, s42, 0x100
	v_mov_b32_e32 v0, 0
	s_addc_u32 vcc_hi, s43, 0
	s_mov_b32 s42, 0
	s_add_i32 s94, s42, 2
	s_add_u32 s44, s0, 0x80
	s_addc_u32 s43, s1, 0
	s_add_i32 s95, 0, 0x10000
	v_add_u32_e32 v140, s95, v173
	ds_read_b128 v[128:131], v140
	ds_read_b128 v[132:135], v140 offset:1024
	ds_read_b128 v[136:139], v140 offset:2048
	ds_read_b128 v[140:143], v140 offset:3072
	s_cmp_eq_u32 s79, s42
	s_cselect_b32 s42, s20, s44
	s_cselect_b32 s43, s21, s43
	s_cselect_b32 s45, s41, vcc_hi
	s_cselect_b32 s44, s40, vcc_lo
	v_lshl_add_u64 v[216:217], s[0:1], 0, v[164:165]
	s_add_i32 m0, s51, 0xc000
	ds_read_b128 v[168:171], v175
	ds_read_b128 v[192:195], v175 offset:2048
	ds_read_b128 v[200:203], v175 offset:4096
	ds_read_b128 v[208:211], v175 offset:6144
	ds_read_b128 v[188:191], v175 offset:1024
	ds_read_b128 v[196:199], v175 offset:3072
	ds_read_b128 v[204:207], v175 offset:5120
	ds_read_b128 v[212:215], v175 offset:7168
	global_load_lds_dwordx4 v[216:217], off
	v_lshl_add_u64 v[216:217], s[0:1], 0, v[166:167]
	s_add_i32 m0, s51, 0xe000
	s_nop 0
	global_load_lds_dwordx4 v[216:217], off
	s_waitcnt lgkmcnt(8)
	s_barrier
	s_setprio 1
	s_waitcnt lgkmcnt(7)
	v_mfma_f32_16x16x32_bf16 v[124:127], v[128:131], v[168:171], 0
	v_mfma_f32_16x16x32_bf16 v[120:123], v[136:139], v[168:171], 0
	s_waitcnt lgkmcnt(6)
	v_mfma_f32_16x16x32_bf16 v[112:115], v[128:131], v[192:195], 0
	v_mfma_f32_16x16x32_bf16 v[104:107], v[136:139], v[192:195], 0
	s_waitcnt lgkmcnt(5)
	v_mfma_f32_16x16x32_bf16 v[96:99], v[128:131], v[200:203], 0
	v_mfma_f32_16x16x32_bf16 v[88:91], v[136:139], v[200:203], 0
	s_waitcnt lgkmcnt(4)
	v_mfma_f32_16x16x32_bf16 v[80:83], v[128:131], v[208:211], 0
	v_mfma_f32_16x16x32_bf16 v[72:75], v[136:139], v[208:211], 0
	s_waitcnt lgkmcnt(3)
	v_mfma_f32_16x16x32_bf16 v[124:127], v[132:135], v[188:191], v[124:127]
	v_mfma_f32_16x16x32_bf16 v[120:123], v[140:143], v[188:191], v[120:123]
	s_waitcnt lgkmcnt(2)
	v_mfma_f32_16x16x32_bf16 v[112:115], v[132:135], v[196:199], v[112:115]
	v_mfma_f32_16x16x32_bf16 v[104:107], v[140:143], v[196:199], v[104:107]
	s_waitcnt lgkmcnt(1)
	v_mfma_f32_16x16x32_bf16 v[96:99], v[132:135], v[204:207], v[96:99]
	v_mfma_f32_16x16x32_bf16 v[88:91], v[140:143], v[204:207], v[88:91]
	s_waitcnt lgkmcnt(0)
	v_mfma_f32_16x16x32_bf16 v[80:83], v[132:135], v[212:215], v[80:83]
	v_mfma_f32_16x16x32_bf16 v[72:75], v[140:143], v[212:215], v[72:75]
	s_setprio 0
	s_barrier
	s_add_i32 s96, 0, 0x14000
	s_add_i32 s95, s95, s50
	v_add_u32_e32 v228, s96, v173
	v_lshl_add_u64 v[232:233], s[44:45], 0, v[148:149]
	s_mov_b32 m0, s95
	ds_read_b128 v[216:219], v228
	ds_read_b128 v[220:223], v228 offset:1024
	ds_read_b128 v[224:227], v228 offset:2048
	ds_read_b128 v[228:231], v228 offset:3072
	global_load_lds_dwordx4 v[232:233], off
	v_lshl_add_u64 v[234:235], s[44:45], 0, v[158:159]
	s_add_i32 m0, s95, 0x2000
	s_nop 0
	global_load_lds_dwordx4 v[234:235], off
	s_barrier
	s_setprio 1
	s_waitcnt lgkmcnt(3)
	v_mfma_f32_16x16x32_bf16 v[116:119], v[216:219], v[168:171], 0
	s_waitcnt lgkmcnt(1)
	v_mfma_f32_16x16x32_bf16 v[108:111], v[224:227], v[168:171], 0
	v_mfma_f32_16x16x32_bf16 v[100:103], v[216:219], v[192:195], 0
	v_mfma_f32_16x16x32_bf16 v[92:95], v[224:227], v[192:195], 0
	v_mfma_f32_16x16x32_bf16 v[84:87], v[216:219], v[200:203], 0
	v_mfma_f32_16x16x32_bf16 v[76:79], v[224:227], v[200:203], 0
	v_mfma_f32_16x16x32_bf16 v[68:71], v[216:219], v[208:211], 0
	v_mfma_f32_16x16x32_bf16 v[64:67], v[224:227], v[208:211], 0
	v_mfma_f32_16x16x32_bf16 v[116:119], v[220:223], v[188:191], v[116:119]
	s_waitcnt lgkmcnt(0)
	v_mfma_f32_16x16x32_bf16 v[108:111], v[228:231], v[188:191], v[108:111]
	v_mfma_f32_16x16x32_bf16 v[100:103], v[220:223], v[196:199], v[100:103]
	v_mfma_f32_16x16x32_bf16 v[92:95], v[228:231], v[196:199], v[92:95]
	v_mfma_f32_16x16x32_bf16 v[84:87], v[220:223], v[204:207], v[84:87]
	v_mfma_f32_16x16x32_bf16 v[76:79], v[228:231], v[204:207], v[76:79]
	v_mfma_f32_16x16x32_bf16 v[68:71], v[220:223], v[212:215], v[68:71]
	v_mfma_f32_16x16x32_bf16 v[64:67], v[228:231], v[212:215], v[64:67]
	s_setprio 0
	s_mov_b32 m0, s51
	v_lshl_add_u64 v[236:237], s[42:43], 0, v[162:163]
	s_barrier
	ds_read_b128 v[168:171], v175 offset:16384
	ds_read_b128 v[192:195], v175 offset:18432
	ds_read_b128 v[200:203], v175 offset:20480
	ds_read_b128 v[208:211], v175 offset:22528
	ds_read_b128 v[188:191], v175 offset:17408
	ds_read_b128 v[196:199], v175 offset:19456
	ds_read_b128 v[204:207], v175 offset:21504
	ds_read_b128 v[212:215], v175 offset:23552
	global_load_lds_dwordx4 v[236:237], off
	v_lshl_add_u64 v[238:239], s[42:43], 0, v[160:161]
	s_mov_b32 m0, s74
	s_nop 0
	global_load_lds_dwordx4 v[238:239], off
	s_barrier
	s_setprio 1
	s_waitcnt lgkmcnt(7)
	v_mfma_f32_16x16x32_bf16 v[60:63], v[128:131], v[168:171], 0
	v_mfma_f32_16x16x32_bf16 v[56:59], v[136:139], v[168:171], 0
	s_waitcnt lgkmcnt(6)
	v_mfma_f32_16x16x32_bf16 v[52:55], v[128:131], v[192:195], 0
	v_mfma_f32_16x16x32_bf16 v[44:47], v[136:139], v[192:195], 0
	s_waitcnt lgkmcnt(5)
	v_mfma_f32_16x16x32_bf16 v[36:39], v[128:131], v[200:203], 0
	v_mfma_f32_16x16x32_bf16 v[28:31], v[136:139], v[200:203], 0
	s_waitcnt lgkmcnt(4)
	v_mfma_f32_16x16x32_bf16 v[20:23], v[128:131], v[208:211], 0
	v_mfma_f32_16x16x32_bf16 v[12:15], v[136:139], v[208:211], 0
	s_waitcnt lgkmcnt(3)
	v_mfma_f32_16x16x32_bf16 v[60:63], v[132:135], v[188:191], v[60:63]
	v_mfma_f32_16x16x32_bf16 v[56:59], v[140:143], v[188:191], v[56:59]
	s_waitcnt lgkmcnt(2)
	v_mfma_f32_16x16x32_bf16 v[52:55], v[132:135], v[196:199], v[52:55]
	v_mfma_f32_16x16x32_bf16 v[44:47], v[140:143], v[196:199], v[44:47]
	s_waitcnt lgkmcnt(1)
	v_mfma_f32_16x16x32_bf16 v[36:39], v[132:135], v[204:207], v[36:39]
	v_mfma_f32_16x16x32_bf16 v[28:31], v[140:143], v[204:207], v[28:31]
	s_waitcnt lgkmcnt(0)
	v_mfma_f32_16x16x32_bf16 v[20:23], v[132:135], v[212:215], v[20:23]
	v_mfma_f32_16x16x32_bf16 v[12:15], v[140:143], v[212:215], v[12:15]
	s_setprio 0
	s_barrier
	s_add_u32 s44, s44, s11
	s_addc_u32 s45, s45, 0
	s_add_i32 s95, s96, s50
	v_lshl_add_u64 v[240:241], s[44:45], 0, v[148:149]
	s_mov_b32 m0, s95
	v_lshl_add_u64 v[242:243], s[44:45], 0, v[158:159]
	global_load_lds_dwordx4 v[240:241], off
	s_add_i32 m0, s95, 0x2000
	s_nop 0
	global_load_lds_dwordx4 v[242:243], off
	s_waitcnt vmcnt(6)
	s_barrier
	s_setprio 1
	v_mfma_f32_16x16x32_bf16 v[48:51], v[216:219], v[168:171], 0
	v_mfma_f32_16x16x32_bf16 v[40:43], v[224:227], v[168:171], 0
	v_mfma_f32_16x16x32_bf16 v[32:35], v[216:219], v[192:195], 0
	v_mfma_f32_16x16x32_bf16 v[24:27], v[224:227], v[192:195], 0
	v_mfma_f32_16x16x32_bf16 v[16:19], v[216:219], v[200:203], 0
	v_mfma_f32_16x16x32_bf16 v[8:11], v[224:227], v[200:203], 0
	v_mfma_f32_16x16x32_bf16 v[4:7], v[216:219], v[208:211], 0
	v_mfma_f32_16x16x32_bf16 v[0:3], v[224:227], v[208:211], 0
	v_mfma_f32_16x16x32_bf16 v[48:51], v[220:223], v[188:191], v[48:51]
	v_mfma_f32_16x16x32_bf16 v[40:43], v[228:231], v[188:191], v[40:43]
	v_mfma_f32_16x16x32_bf16 v[32:35], v[220:223], v[196:199], v[32:35]
	v_mfma_f32_16x16x32_bf16 v[24:27], v[228:231], v[196:199], v[24:27]
	v_mfma_f32_16x16x32_bf16 v[16:19], v[220:223], v[204:207], v[16:19]
	v_mfma_f32_16x16x32_bf16 v[8:11], v[228:231], v[204:207], v[8:11]
	v_mfma_f32_16x16x32_bf16 v[4:7], v[220:223], v[212:215], v[4:7]
	v_mfma_f32_16x16x32_bf16 v[0:3], v[228:231], v[212:215], v[0:3]
	s_setprio 0
	s_add_i32 s44, 0, 0x18000
	v_add_u32_e32 v140, s44, v173
	s_barrier
	ds_read_b128 v[128:131], v140
	ds_read_b128 v[132:135], v140 offset:1024
	ds_read_b128 v[136:139], v140 offset:2048
	ds_read_b128 v[140:143], v140 offset:3072
	s_add_u32 s42, s42, s84
	s_addc_u32 s43, s43, 0
	s_mov_b32 m0, s75
	v_lshl_add_u64 v[216:217], s[42:43], 0, v[162:163]
	ds_read_b128 v[168:171], v175 offset:32768
	ds_read_b128 v[192:195], v175 offset:34816
	ds_read_b128 v[200:203], v175 offset:36864
	ds_read_b128 v[208:211], v175 offset:38912
	ds_read_b128 v[188:191], v175 offset:33792
	ds_read_b128 v[196:199], v175 offset:35840
	ds_read_b128 v[204:207], v175 offset:37888
	ds_read_b128 v[212:215], v175 offset:39936
	global_load_lds_dwordx4 v[216:217], off
	v_lshl_add_u64 v[216:217], s[42:43], 0, v[160:161]
	s_mov_b32 m0, s78
	s_nop 0
	global_load_lds_dwordx4 v[216:217], off
	s_waitcnt lgkmcnt(8)
	s_barrier
	s_setprio 1
	s_waitcnt lgkmcnt(7)
	v_mfma_f32_16x16x32_bf16 v[124:127], v[128:131], v[168:171], v[124:127]
	v_mfma_f32_16x16x32_bf16 v[120:123], v[136:139], v[168:171], v[120:123]
	s_waitcnt lgkmcnt(6)
	v_mfma_f32_16x16x32_bf16 v[112:115], v[128:131], v[192:195], v[112:115]
	v_mfma_f32_16x16x32_bf16 v[104:107], v[136:139], v[192:195], v[104:107]
	s_waitcnt lgkmcnt(5)
	v_mfma_f32_16x16x32_bf16 v[96:99], v[128:131], v[200:203], v[96:99]
	v_mfma_f32_16x16x32_bf16 v[88:91], v[136:139], v[200:203], v[88:91]
	s_waitcnt lgkmcnt(4)
	v_mfma_f32_16x16x32_bf16 v[80:83], v[128:131], v[208:211], v[80:83]
	v_mfma_f32_16x16x32_bf16 v[72:75], v[136:139], v[208:211], v[72:75]
	s_waitcnt lgkmcnt(3)
	v_mfma_f32_16x16x32_bf16 v[124:127], v[132:135], v[188:191], v[124:127]
	v_mfma_f32_16x16x32_bf16 v[120:123], v[140:143], v[188:191], v[120:123]
	s_waitcnt lgkmcnt(2)
	v_mfma_f32_16x16x32_bf16 v[112:115], v[132:135], v[196:199], v[112:115]
	v_mfma_f32_16x16x32_bf16 v[104:107], v[140:143], v[196:199], v[104:107]
	s_waitcnt lgkmcnt(1)
	v_mfma_f32_16x16x32_bf16 v[96:99], v[132:135], v[204:207], v[96:99]
	v_mfma_f32_16x16x32_bf16 v[88:91], v[140:143], v[204:207], v[88:91]
	s_waitcnt lgkmcnt(0)
	v_mfma_f32_16x16x32_bf16 v[80:83], v[132:135], v[212:215], v[80:83]
	v_mfma_f32_16x16x32_bf16 v[72:75], v[140:143], v[212:215], v[72:75]
	s_setprio 0
	s_barrier
	s_add_i32 s42, 0, 0x1c000
	s_add_i32 s43, s44, s50
	v_add_u32_e32 v228, s42, v173
	v_lshl_add_u64 v[232:233], v[232:233], 0, s[28:29]
	s_mov_b32 m0, s43
	ds_read_b128 v[216:219], v228
	ds_read_b128 v[220:223], v228 offset:1024
	ds_read_b128 v[224:227], v228 offset:2048
	ds_read_b128 v[228:231], v228 offset:3072
	global_load_lds_dwordx4 v[232:233], off
	v_lshl_add_u64 v[232:233], v[234:235], 0, s[28:29]
	s_add_i32 m0, s43, 0x2000
	s_nop 0
	global_load_lds_dwordx4 v[232:233], off
	s_barrier
	s_setprio 1
	s_waitcnt lgkmcnt(3)
	v_mfma_f32_16x16x32_bf16 v[116:119], v[216:219], v[168:171], v[116:119]
	s_waitcnt lgkmcnt(1)
	v_mfma_f32_16x16x32_bf16 v[108:111], v[224:227], v[168:171], v[108:111]
	v_mfma_f32_16x16x32_bf16 v[100:103], v[216:219], v[192:195], v[100:103]
	v_mfma_f32_16x16x32_bf16 v[92:95], v[224:227], v[192:195], v[92:95]
	v_mfma_f32_16x16x32_bf16 v[84:87], v[216:219], v[200:203], v[84:87]
	v_mfma_f32_16x16x32_bf16 v[76:79], v[224:227], v[200:203], v[76:79]
	v_mfma_f32_16x16x32_bf16 v[68:71], v[216:219], v[208:211], v[68:71]
	v_mfma_f32_16x16x32_bf16 v[64:67], v[224:227], v[208:211], v[64:67]
	v_mfma_f32_16x16x32_bf16 v[116:119], v[220:223], v[188:191], v[116:119]
	s_waitcnt lgkmcnt(0)
	v_mfma_f32_16x16x32_bf16 v[108:111], v[228:231], v[188:191], v[108:111]
	v_mfma_f32_16x16x32_bf16 v[100:103], v[220:223], v[196:199], v[100:103]
	v_mfma_f32_16x16x32_bf16 v[92:95], v[228:231], v[196:199], v[92:95]
	v_mfma_f32_16x16x32_bf16 v[84:87], v[220:223], v[204:207], v[84:87]
	v_mfma_f32_16x16x32_bf16 v[76:79], v[228:231], v[204:207], v[76:79]
	v_mfma_f32_16x16x32_bf16 v[68:71], v[220:223], v[212:215], v[68:71]
	v_mfma_f32_16x16x32_bf16 v[64:67], v[228:231], v[212:215], v[64:67]
	s_setprio 0
	s_mov_b32 m0, s80
	v_lshl_add_u64 v[232:233], v[236:237], 0, s[28:29]
	s_barrier
	ds_read_b128 v[168:171], v175 offset:49152
	ds_read_b128 v[192:195], v175 offset:51200
	ds_read_b128 v[200:203], v175 offset:53248
	ds_read_b128 v[208:211], v175 offset:55296
	ds_read_b128 v[188:191], v175 offset:50176
	ds_read_b128 v[196:199], v175 offset:52224
	ds_read_b128 v[204:207], v175 offset:54272
	ds_read_b128 v[212:215], v175 offset:56320
	global_load_lds_dwordx4 v[232:233], off
	v_lshl_add_u64 v[232:233], v[238:239], 0, s[28:29]
	s_mov_b32 m0, s81
	s_nop 0
	global_load_lds_dwordx4 v[232:233], off
	s_barrier
	s_setprio 1
	s_waitcnt lgkmcnt(7)
	v_mfma_f32_16x16x32_bf16 v[60:63], v[128:131], v[168:171], v[60:63]
	v_mfma_f32_16x16x32_bf16 v[56:59], v[136:139], v[168:171], v[56:59]
	s_waitcnt lgkmcnt(6)
	v_mfma_f32_16x16x32_bf16 v[52:55], v[128:131], v[192:195], v[52:55]
	v_mfma_f32_16x16x32_bf16 v[44:47], v[136:139], v[192:195], v[44:47]
	s_waitcnt lgkmcnt(5)
	v_mfma_f32_16x16x32_bf16 v[36:39], v[128:131], v[200:203], v[36:39]
	v_mfma_f32_16x16x32_bf16 v[28:31], v[136:139], v[200:203], v[28:31]
	s_waitcnt lgkmcnt(4)
	v_mfma_f32_16x16x32_bf16 v[20:23], v[128:131], v[208:211], v[20:23]
	v_mfma_f32_16x16x32_bf16 v[12:15], v[136:139], v[208:211], v[12:15]
	s_waitcnt lgkmcnt(3)
	v_mfma_f32_16x16x32_bf16 v[60:63], v[132:135], v[188:191], v[60:63]
	v_mfma_f32_16x16x32_bf16 v[56:59], v[140:143], v[188:191], v[56:59]
	s_waitcnt lgkmcnt(2)
	v_mfma_f32_16x16x32_bf16 v[52:55], v[132:135], v[196:199], v[52:55]
	v_mfma_f32_16x16x32_bf16 v[44:47], v[140:143], v[196:199], v[44:47]
	s_waitcnt lgkmcnt(1)
	v_mfma_f32_16x16x32_bf16 v[36:39], v[132:135], v[204:207], v[36:39]
	v_mfma_f32_16x16x32_bf16 v[28:31], v[140:143], v[204:207], v[28:31]
	s_waitcnt lgkmcnt(0)
	v_mfma_f32_16x16x32_bf16 v[20:23], v[132:135], v[212:215], v[20:23]
	v_mfma_f32_16x16x32_bf16 v[12:15], v[140:143], v[212:215], v[12:15]
	s_setprio 0
	s_barrier
	s_add_i32 s42, s42, s50
	v_lshl_add_u64 v[128:129], v[240:241], 0, s[28:29]
	s_mov_b32 m0, s42
	s_nop 0
	global_load_lds_dwordx4 v[128:129], off
	v_lshl_add_u64 v[128:129], v[242:243], 0, s[28:29]
	s_add_i32 m0, s42, 0x2000
	s_nop 0
	global_load_lds_dwordx4 v[128:129], off
	s_waitcnt vmcnt(6)
	s_barrier
	s_setprio 1
	v_mfma_f32_16x16x32_bf16 v[48:51], v[216:219], v[168:171], v[48:51]
	v_mfma_f32_16x16x32_bf16 v[40:43], v[224:227], v[168:171], v[40:43]
	v_mfma_f32_16x16x32_bf16 v[32:35], v[216:219], v[192:195], v[32:35]
	v_mfma_f32_16x16x32_bf16 v[24:27], v[224:227], v[192:195], v[24:27]
	v_mfma_f32_16x16x32_bf16 v[16:19], v[216:219], v[200:203], v[16:19]
	v_mfma_f32_16x16x32_bf16 v[8:11], v[224:227], v[200:203], v[8:11]
	v_mfma_f32_16x16x32_bf16 v[4:7], v[216:219], v[208:211], v[4:7]
	v_mfma_f32_16x16x32_bf16 v[0:3], v[224:227], v[208:211], v[0:3]
	v_mfma_f32_16x16x32_bf16 v[48:51], v[220:223], v[188:191], v[48:51]
	v_mfma_f32_16x16x32_bf16 v[40:43], v[228:231], v[188:191], v[40:43]
	v_mfma_f32_16x16x32_bf16 v[32:35], v[220:223], v[196:199], v[32:35]
	v_mfma_f32_16x16x32_bf16 v[24:27], v[228:231], v[196:199], v[24:27]
	v_mfma_f32_16x16x32_bf16 v[16:19], v[220:223], v[204:207], v[16:19]
	v_mfma_f32_16x16x32_bf16 v[8:11], v[228:231], v[204:207], v[8:11]
	v_mfma_f32_16x16x32_bf16 v[4:7], v[220:223], v[212:215], v[4:7]
	v_mfma_f32_16x16x32_bf16 v[0:3], v[228:231], v[212:215], v[0:3]
	s_setprio 0
	s_add_u32 s0, s0, 0x100
	s_addc_u32 s1, s1, 0
	s_add_u32 vcc_lo, vcc_lo, 0x100
	s_addc_u32 vcc_hi, vcc_hi, 0
	s_cmp_ge_u32 s94, s88
	s_mov_b32 s42, s94
	s_barrier
	s_cbranch_scc1 .Lpeel_after_g2
.LBB0_490:
	s_add_i32 s94, s42, 2
	s_add_u32 s44, s0, 0x80
	s_addc_u32 s43, s1, 0
	s_add_i32 s95, 0, 0x10000
	v_add_u32_e32 v140, s95, v173
	ds_read_b128 v[128:131], v140
	ds_read_b128 v[132:135], v140 offset:1024
	ds_read_b128 v[136:139], v140 offset:2048
	ds_read_b128 v[140:143], v140 offset:3072
	s_cmp_eq_u32 s79, s42
	s_cselect_b32 s42, s20, s44
	s_cselect_b32 s43, s21, s43
	s_cselect_b32 s45, s41, vcc_hi
	s_cselect_b32 s44, s40, vcc_lo
	v_lshl_add_u64 v[216:217], s[0:1], 0, v[164:165]
	s_add_i32 m0, s51, 0xc000
	ds_read_b128 v[168:171], v175
	ds_read_b128 v[192:195], v175 offset:2048
	ds_read_b128 v[200:203], v175 offset:4096
	ds_read_b128 v[208:211], v175 offset:6144
	ds_read_b128 v[188:191], v175 offset:1024
	ds_read_b128 v[196:199], v175 offset:3072
	ds_read_b128 v[204:207], v175 offset:5120
	ds_read_b128 v[212:215], v175 offset:7168
	global_load_lds_dwordx4 v[216:217], off
	v_lshl_add_u64 v[216:217], s[0:1], 0, v[166:167]
	s_add_i32 m0, s51, 0xe000
	s_nop 0
	global_load_lds_dwordx4 v[216:217], off
	s_waitcnt lgkmcnt(8)
	s_barrier
	s_setprio 1
	s_waitcnt lgkmcnt(7)
	v_mfma_f32_16x16x32_bf16 v[124:127], v[128:131], v[168:171], v[124:127]
	v_mfma_f32_16x16x32_bf16 v[120:123], v[136:139], v[168:171], v[120:123]
	s_waitcnt lgkmcnt(6)
	v_mfma_f32_16x16x32_bf16 v[112:115], v[128:131], v[192:195], v[112:115]
	v_mfma_f32_16x16x32_bf16 v[104:107], v[136:139], v[192:195], v[104:107]
	s_waitcnt lgkmcnt(5)
	v_mfma_f32_16x16x32_bf16 v[96:99], v[128:131], v[200:203], v[96:99]
	v_mfma_f32_16x16x32_bf16 v[88:91], v[136:139], v[200:203], v[88:91]
	s_waitcnt lgkmcnt(4)
	v_mfma_f32_16x16x32_bf16 v[80:83], v[128:131], v[208:211], v[80:83]
	v_mfma_f32_16x16x32_bf16 v[72:75], v[136:139], v[208:211], v[72:75]
	s_waitcnt lgkmcnt(3)
	v_mfma_f32_16x16x32_bf16 v[124:127], v[132:135], v[188:191], v[124:127]
	v_mfma_f32_16x16x32_bf16 v[120:123], v[140:143], v[188:191], v[120:123]
	s_waitcnt lgkmcnt(2)
	v_mfma_f32_16x16x32_bf16 v[112:115], v[132:135], v[196:199], v[112:115]
	v_mfma_f32_16x16x32_bf16 v[104:107], v[140:143], v[196:199], v[104:107]
	s_waitcnt lgkmcnt(1)
	v_mfma_f32_16x16x32_bf16 v[96:99], v[132:135], v[204:207], v[96:99]
	v_mfma_f32_16x16x32_bf16 v[88:91], v[140:143], v[204:207], v[88:91]
	s_waitcnt lgkmcnt(0)
	v_mfma_f32_16x16x32_bf16 v[80:83], v[132:135], v[212:215], v[80:83]
	v_mfma_f32_16x16x32_bf16 v[72:75], v[140:143], v[212:215], v[72:75]
	s_setprio 0
	s_barrier
	s_add_i32 s96, 0, 0x14000
	s_add_i32 s95, s95, s50
	v_add_u32_e32 v228, s96, v173
	v_lshl_add_u64 v[232:233], s[44:45], 0, v[148:149]
	s_mov_b32 m0, s95
	ds_read_b128 v[216:219], v228
	ds_read_b128 v[220:223], v228 offset:1024
	ds_read_b128 v[224:227], v228 offset:2048
	ds_read_b128 v[228:231], v228 offset:3072
	global_load_lds_dwordx4 v[232:233], off
	v_lshl_add_u64 v[234:235], s[44:45], 0, v[158:159]
	s_add_i32 m0, s95, 0x2000
	s_nop 0
	global_load_lds_dwordx4 v[234:235], off
	s_barrier
	s_setprio 1
	s_waitcnt lgkmcnt(3)
	v_mfma_f32_16x16x32_bf16 v[116:119], v[216:219], v[168:171], v[116:119]
	s_waitcnt lgkmcnt(1)
	v_mfma_f32_16x16x32_bf16 v[108:111], v[224:227], v[168:171], v[108:111]
	v_mfma_f32_16x16x32_bf16 v[100:103], v[216:219], v[192:195], v[100:103]
	v_mfma_f32_16x16x32_bf16 v[92:95], v[224:227], v[192:195], v[92:95]
	v_mfma_f32_16x16x32_bf16 v[84:87], v[216:219], v[200:203], v[84:87]
	v_mfma_f32_16x16x32_bf16 v[76:79], v[224:227], v[200:203], v[76:79]
	v_mfma_f32_16x16x32_bf16 v[68:71], v[216:219], v[208:211], v[68:71]
	v_mfma_f32_16x16x32_bf16 v[64:67], v[224:227], v[208:211], v[64:67]
	v_mfma_f32_16x16x32_bf16 v[116:119], v[220:223], v[188:191], v[116:119]
	s_waitcnt lgkmcnt(0)
	v_mfma_f32_16x16x32_bf16 v[108:111], v[228:231], v[188:191], v[108:111]
	v_mfma_f32_16x16x32_bf16 v[100:103], v[220:223], v[196:199], v[100:103]
	v_mfma_f32_16x16x32_bf16 v[92:95], v[228:231], v[196:199], v[92:95]
	v_mfma_f32_16x16x32_bf16 v[84:87], v[220:223], v[204:207], v[84:87]
	v_mfma_f32_16x16x32_bf16 v[76:79], v[228:231], v[204:207], v[76:79]
	v_mfma_f32_16x16x32_bf16 v[68:71], v[220:223], v[212:215], v[68:71]
	v_mfma_f32_16x16x32_bf16 v[64:67], v[228:231], v[212:215], v[64:67]
	s_setprio 0
	s_mov_b32 m0, s51
	v_lshl_add_u64 v[236:237], s[42:43], 0, v[162:163]
	s_barrier
	ds_read_b128 v[168:171], v175 offset:16384
	ds_read_b128 v[192:195], v175 offset:18432
	ds_read_b128 v[200:203], v175 offset:20480
	ds_read_b128 v[208:211], v175 offset:22528
	ds_read_b128 v[188:191], v175 offset:17408
	ds_read_b128 v[196:199], v175 offset:19456
	ds_read_b128 v[204:207], v175 offset:21504
	ds_read_b128 v[212:215], v175 offset:23552
	global_load_lds_dwordx4 v[236:237], off
	v_lshl_add_u64 v[238:239], s[42:43], 0, v[160:161]
	s_mov_b32 m0, s74
	s_nop 0
	global_load_lds_dwordx4 v[238:239], off
	s_barrier
	s_setprio 1
	s_waitcnt lgkmcnt(7)
	v_mfma_f32_16x16x32_bf16 v[60:63], v[128:131], v[168:171], v[60:63]
	v_mfma_f32_16x16x32_bf16 v[56:59], v[136:139], v[168:171], v[56:59]
	s_waitcnt lgkmcnt(6)
	v_mfma_f32_16x16x32_bf16 v[52:55], v[128:131], v[192:195], v[52:55]
	v_mfma_f32_16x16x32_bf16 v[44:47], v[136:139], v[192:195], v[44:47]
	s_waitcnt lgkmcnt(5)
	v_mfma_f32_16x16x32_bf16 v[36:39], v[128:131], v[200:203], v[36:39]
	v_mfma_f32_16x16x32_bf16 v[28:31], v[136:139], v[200:203], v[28:31]
	s_waitcnt lgkmcnt(4)
	v_mfma_f32_16x16x32_bf16 v[20:23], v[128:131], v[208:211], v[20:23]
	v_mfma_f32_16x16x32_bf16 v[12:15], v[136:139], v[208:211], v[12:15]
	s_waitcnt lgkmcnt(3)
	v_mfma_f32_16x16x32_bf16 v[60:63], v[132:135], v[188:191], v[60:63]
	v_mfma_f32_16x16x32_bf16 v[56:59], v[140:143], v[188:191], v[56:59]
	s_waitcnt lgkmcnt(2)
	v_mfma_f32_16x16x32_bf16 v[52:55], v[132:135], v[196:199], v[52:55]
	v_mfma_f32_16x16x32_bf16 v[44:47], v[140:143], v[196:199], v[44:47]
	s_waitcnt lgkmcnt(1)
	v_mfma_f32_16x16x32_bf16 v[36:39], v[132:135], v[204:207], v[36:39]
	v_mfma_f32_16x16x32_bf16 v[28:31], v[140:143], v[204:207], v[28:31]
	s_waitcnt lgkmcnt(0)
	v_mfma_f32_16x16x32_bf16 v[20:23], v[132:135], v[212:215], v[20:23]
	v_mfma_f32_16x16x32_bf16 v[12:15], v[140:143], v[212:215], v[12:15]
	s_setprio 0
	s_barrier
	s_add_u32 s44, s44, s11
	s_addc_u32 s45, s45, 0
	s_add_i32 s95, s96, s50
	v_lshl_add_u64 v[240:241], s[44:45], 0, v[148:149]
	s_mov_b32 m0, s95
	v_lshl_add_u64 v[242:243], s[44:45], 0, v[158:159]
	global_load_lds_dwordx4 v[240:241], off
	s_add_i32 m0, s95, 0x2000
	s_nop 0
	global_load_lds_dwordx4 v[242:243], off
	s_waitcnt vmcnt(6)
	s_barrier
	s_setprio 1
	v_mfma_f32_16x16x32_bf16 v[48:51], v[216:219], v[168:171], v[48:51]
	v_mfma_f32_16x16x32_bf16 v[40:43], v[224:227], v[168:171], v[40:43]
	v_mfma_f32_16x16x32_bf16 v[32:35], v[216:219], v[192:195], v[32:35]
	v_mfma_f32_16x16x32_bf16 v[24:27], v[224:227], v[192:195], v[24:27]
	v_mfma_f32_16x16x32_bf16 v[16:19], v[216:219], v[200:203], v[16:19]
	v_mfma_f32_16x16x32_bf16 v[8:11], v[224:227], v[200:203], v[8:11]
	v_mfma_f32_16x16x32_bf16 v[4:7], v[216:219], v[208:211], v[4:7]
	v_mfma_f32_16x16x32_bf16 v[0:3], v[224:227], v[208:211], v[0:3]
	v_mfma_f32_16x16x32_bf16 v[48:51], v[220:223], v[188:191], v[48:51]
	v_mfma_f32_16x16x32_bf16 v[40:43], v[228:231], v[188:191], v[40:43]
	v_mfma_f32_16x16x32_bf16 v[32:35], v[220:223], v[196:199], v[32:35]
	v_mfma_f32_16x16x32_bf16 v[24:27], v[228:231], v[196:199], v[24:27]
	v_mfma_f32_16x16x32_bf16 v[16:19], v[220:223], v[204:207], v[16:19]
	v_mfma_f32_16x16x32_bf16 v[8:11], v[228:231], v[204:207], v[8:11]
	v_mfma_f32_16x16x32_bf16 v[4:7], v[220:223], v[212:215], v[4:7]
	v_mfma_f32_16x16x32_bf16 v[0:3], v[228:231], v[212:215], v[0:3]
	s_setprio 0
	s_add_i32 s44, 0, 0x18000
	v_add_u32_e32 v140, s44, v173
	s_barrier
	ds_read_b128 v[128:131], v140
	ds_read_b128 v[132:135], v140 offset:1024
	ds_read_b128 v[136:139], v140 offset:2048
	ds_read_b128 v[140:143], v140 offset:3072
	s_add_u32 s42, s42, s84
	s_addc_u32 s43, s43, 0
	s_mov_b32 m0, s75
	v_lshl_add_u64 v[216:217], s[42:43], 0, v[162:163]
	ds_read_b128 v[168:171], v175 offset:32768
	ds_read_b128 v[192:195], v175 offset:34816
	ds_read_b128 v[200:203], v175 offset:36864
	ds_read_b128 v[208:211], v175 offset:38912
	ds_read_b128 v[188:191], v175 offset:33792
	ds_read_b128 v[196:199], v175 offset:35840
	ds_read_b128 v[204:207], v175 offset:37888
	ds_read_b128 v[212:215], v175 offset:39936
	global_load_lds_dwordx4 v[216:217], off
	v_lshl_add_u64 v[216:217], s[42:43], 0, v[160:161]
	s_mov_b32 m0, s78
	s_nop 0
	global_load_lds_dwordx4 v[216:217], off
	s_waitcnt lgkmcnt(8)
	s_barrier
	s_setprio 1
	s_waitcnt lgkmcnt(7)
	v_mfma_f32_16x16x32_bf16 v[124:127], v[128:131], v[168:171], v[124:127]
	v_mfma_f32_16x16x32_bf16 v[120:123], v[136:139], v[168:171], v[120:123]
	s_waitcnt lgkmcnt(6)
	v_mfma_f32_16x16x32_bf16 v[112:115], v[128:131], v[192:195], v[112:115]
	v_mfma_f32_16x16x32_bf16 v[104:107], v[136:139], v[192:195], v[104:107]
	s_waitcnt lgkmcnt(5)
	v_mfma_f32_16x16x32_bf16 v[96:99], v[128:131], v[200:203], v[96:99]
	v_mfma_f32_16x16x32_bf16 v[88:91], v[136:139], v[200:203], v[88:91]
	s_waitcnt lgkmcnt(4)
	v_mfma_f32_16x16x32_bf16 v[80:83], v[128:131], v[208:211], v[80:83]
	v_mfma_f32_16x16x32_bf16 v[72:75], v[136:139], v[208:211], v[72:75]
	s_waitcnt lgkmcnt(3)
	v_mfma_f32_16x16x32_bf16 v[124:127], v[132:135], v[188:191], v[124:127]
	v_mfma_f32_16x16x32_bf16 v[120:123], v[140:143], v[188:191], v[120:123]
	s_waitcnt lgkmcnt(2)
	v_mfma_f32_16x16x32_bf16 v[112:115], v[132:135], v[196:199], v[112:115]
	v_mfma_f32_16x16x32_bf16 v[104:107], v[140:143], v[196:199], v[104:107]
	s_waitcnt lgkmcnt(1)
	v_mfma_f32_16x16x32_bf16 v[96:99], v[132:135], v[204:207], v[96:99]
	v_mfma_f32_16x16x32_bf16 v[88:91], v[140:143], v[204:207], v[88:91]
	s_waitcnt lgkmcnt(0)
	v_mfma_f32_16x16x32_bf16 v[80:83], v[132:135], v[212:215], v[80:83]
	v_mfma_f32_16x16x32_bf16 v[72:75], v[140:143], v[212:215], v[72:75]
	s_setprio 0
	s_barrier
	s_add_i32 s42, 0, 0x1c000
	s_add_i32 s43, s44, s50
	v_add_u32_e32 v228, s42, v173
	v_lshl_add_u64 v[232:233], v[232:233], 0, s[28:29]
	s_mov_b32 m0, s43
	ds_read_b128 v[216:219], v228
	ds_read_b128 v[220:223], v228 offset:1024
	ds_read_b128 v[224:227], v228 offset:2048
	ds_read_b128 v[228:231], v228 offset:3072
	global_load_lds_dwordx4 v[232:233], off
	v_lshl_add_u64 v[232:233], v[234:235], 0, s[28:29]
	s_add_i32 m0, s43, 0x2000
	s_nop 0
	global_load_lds_dwordx4 v[232:233], off
	s_barrier
	s_setprio 1
	s_waitcnt lgkmcnt(3)
	v_mfma_f32_16x16x32_bf16 v[116:119], v[216:219], v[168:171], v[116:119]
	s_waitcnt lgkmcnt(1)
	v_mfma_f32_16x16x32_bf16 v[108:111], v[224:227], v[168:171], v[108:111]
	v_mfma_f32_16x16x32_bf16 v[100:103], v[216:219], v[192:195], v[100:103]
	v_mfma_f32_16x16x32_bf16 v[92:95], v[224:227], v[192:195], v[92:95]
	v_mfma_f32_16x16x32_bf16 v[84:87], v[216:219], v[200:203], v[84:87]
	v_mfma_f32_16x16x32_bf16 v[76:79], v[224:227], v[200:203], v[76:79]
	v_mfma_f32_16x16x32_bf16 v[68:71], v[216:219], v[208:211], v[68:71]
	v_mfma_f32_16x16x32_bf16 v[64:67], v[224:227], v[208:211], v[64:67]
	v_mfma_f32_16x16x32_bf16 v[116:119], v[220:223], v[188:191], v[116:119]
	s_waitcnt lgkmcnt(0)
	v_mfma_f32_16x16x32_bf16 v[108:111], v[228:231], v[188:191], v[108:111]
	v_mfma_f32_16x16x32_bf16 v[100:103], v[220:223], v[196:199], v[100:103]
	v_mfma_f32_16x16x32_bf16 v[92:95], v[228:231], v[196:199], v[92:95]
	v_mfma_f32_16x16x32_bf16 v[84:87], v[220:223], v[204:207], v[84:87]
	v_mfma_f32_16x16x32_bf16 v[76:79], v[228:231], v[204:207], v[76:79]
	v_mfma_f32_16x16x32_bf16 v[68:71], v[220:223], v[212:215], v[68:71]
	v_mfma_f32_16x16x32_bf16 v[64:67], v[228:231], v[212:215], v[64:67]
	s_setprio 0
	s_mov_b32 m0, s80
	v_lshl_add_u64 v[232:233], v[236:237], 0, s[28:29]
	s_barrier
	ds_read_b128 v[168:171], v175 offset:49152
	ds_read_b128 v[192:195], v175 offset:51200
	ds_read_b128 v[200:203], v175 offset:53248
	ds_read_b128 v[208:211], v175 offset:55296
	ds_read_b128 v[188:191], v175 offset:50176
	ds_read_b128 v[196:199], v175 offset:52224
	ds_read_b128 v[204:207], v175 offset:54272
	ds_read_b128 v[212:215], v175 offset:56320
	global_load_lds_dwordx4 v[232:233], off
	v_lshl_add_u64 v[232:233], v[238:239], 0, s[28:29]
	s_mov_b32 m0, s81
	s_nop 0
	global_load_lds_dwordx4 v[232:233], off
	s_barrier
	s_setprio 1
	s_waitcnt lgkmcnt(7)
	v_mfma_f32_16x16x32_bf16 v[60:63], v[128:131], v[168:171], v[60:63]
	v_mfma_f32_16x16x32_bf16 v[56:59], v[136:139], v[168:171], v[56:59]
	s_waitcnt lgkmcnt(6)
	v_mfma_f32_16x16x32_bf16 v[52:55], v[128:131], v[192:195], v[52:55]
	v_mfma_f32_16x16x32_bf16 v[44:47], v[136:139], v[192:195], v[44:47]
	s_waitcnt lgkmcnt(5)
	v_mfma_f32_16x16x32_bf16 v[36:39], v[128:131], v[200:203], v[36:39]
	v_mfma_f32_16x16x32_bf16 v[28:31], v[136:139], v[200:203], v[28:31]
	s_waitcnt lgkmcnt(4)
	v_mfma_f32_16x16x32_bf16 v[20:23], v[128:131], v[208:211], v[20:23]
	v_mfma_f32_16x16x32_bf16 v[12:15], v[136:139], v[208:211], v[12:15]
	s_waitcnt lgkmcnt(3)
	v_mfma_f32_16x16x32_bf16 v[60:63], v[132:135], v[188:191], v[60:63]
	v_mfma_f32_16x16x32_bf16 v[56:59], v[140:143], v[188:191], v[56:59]
	s_waitcnt lgkmcnt(2)
	v_mfma_f32_16x16x32_bf16 v[52:55], v[132:135], v[196:199], v[52:55]
	v_mfma_f32_16x16x32_bf16 v[44:47], v[140:143], v[196:199], v[44:47]
	s_waitcnt lgkmcnt(1)
	v_mfma_f32_16x16x32_bf16 v[36:39], v[132:135], v[204:207], v[36:39]
	v_mfma_f32_16x16x32_bf16 v[28:31], v[140:143], v[204:207], v[28:31]
	s_waitcnt lgkmcnt(0)
	v_mfma_f32_16x16x32_bf16 v[20:23], v[132:135], v[212:215], v[20:23]
	v_mfma_f32_16x16x32_bf16 v[12:15], v[140:143], v[212:215], v[12:15]
	s_setprio 0
	s_barrier
	s_add_i32 s42, s42, s50
	v_lshl_add_u64 v[128:129], v[240:241], 0, s[28:29]
	s_mov_b32 m0, s42
	s_nop 0
	global_load_lds_dwordx4 v[128:129], off
	v_lshl_add_u64 v[128:129], v[242:243], 0, s[28:29]
	s_add_i32 m0, s42, 0x2000
	s_nop 0
	global_load_lds_dwordx4 v[128:129], off
	s_waitcnt vmcnt(6)
	s_barrier
	s_setprio 1
	v_mfma_f32_16x16x32_bf16 v[48:51], v[216:219], v[168:171], v[48:51]
	v_mfma_f32_16x16x32_bf16 v[40:43], v[224:227], v[168:171], v[40:43]
	v_mfma_f32_16x16x32_bf16 v[32:35], v[216:219], v[192:195], v[32:35]
	v_mfma_f32_16x16x32_bf16 v[24:27], v[224:227], v[192:195], v[24:27]
	v_mfma_f32_16x16x32_bf16 v[16:19], v[216:219], v[200:203], v[16:19]
	v_mfma_f32_16x16x32_bf16 v[8:11], v[224:227], v[200:203], v[8:11]
	v_mfma_f32_16x16x32_bf16 v[4:7], v[216:219], v[208:211], v[4:7]
	v_mfma_f32_16x16x32_bf16 v[0:3], v[224:227], v[208:211], v[0:3]
	v_mfma_f32_16x16x32_bf16 v[48:51], v[220:223], v[188:191], v[48:51]
	v_mfma_f32_16x16x32_bf16 v[40:43], v[228:231], v[188:191], v[40:43]
	v_mfma_f32_16x16x32_bf16 v[32:35], v[220:223], v[196:199], v[32:35]
	v_mfma_f32_16x16x32_bf16 v[24:27], v[228:231], v[196:199], v[24:27]
	v_mfma_f32_16x16x32_bf16 v[16:19], v[220:223], v[204:207], v[16:19]
	v_mfma_f32_16x16x32_bf16 v[8:11], v[228:231], v[204:207], v[8:11]
	v_mfma_f32_16x16x32_bf16 v[4:7], v[220:223], v[212:215], v[4:7]
	v_mfma_f32_16x16x32_bf16 v[0:3], v[228:231], v[212:215], v[0:3]
	s_setprio 0
	s_add_u32 s0, s0, 0x100
	s_addc_u32 s1, s1, 0
	s_add_u32 vcc_lo, vcc_lo, 0x100
	s_addc_u32 vcc_hi, vcc_hi, 0
	s_cmp_ge_u32 s94, s88
	s_mov_b32 s42, s94
	s_barrier
	s_cbranch_scc0 .LBB0_490

.LBB0_704:
	s_ashr_i32 s3, s2, 31
	v_cmp_lt_i64_e32 vcc, s[4:5], v[152:153]
	s_lshl_b64 s[4:5], s[2:3], 19
	s_add_u32 s4, s68, s4
	s_addc_u32 s5, s69, s5
	s_and_b64 s[8:9], vcc, exec
	s_cselect_b32 s3, s5, s11
	s_cselect_b32 s45, s4, s10
	s_ashr_i32 s1, s0, 31
	s_lshl_b64 s[8:9], s[0:1], 19
	s_add_u32 s8, s65, s8
	s_addc_u32 s9, s72, s9
	s_and_b64 s[20:21], vcc, exec
	s_cselect_b32 s1, s9, s15
	s_cselect_b32 s46, s8, s14
	s_add_u32 s10, s10, 0x40080
	s_addc_u32 s11, s11, 0
	s_add_u32 s47, s14, 0x100
	v_mov_b32_e32 v0, 0
	s_addc_u32 s50, s15, 0
	s_mov_b32 s51, -2
	s_add_u32 s14, s10, 0xfffc0080
	s_addc_u32 s15, s11, -1
	s_add_i32 s73, 0, 0x10000
	v_add_u32_e32 v138, s73, v141
	ds_read_b128 v[158:161], v138
	ds_read_b128 v[162:165], v138 offset:1024
	ds_read_b128 v[166:169], v138 offset:2048
	ds_read_b128 v[170:173], v138 offset:3072
	s_cmp_eq_u32 s51, 12
	s_cselect_b32 s21, s3, s15
	s_cselect_b32 s20, s45, s14
	s_cselect_b32 s15, s1, s50
	s_cselect_b32 s14, s46, s47
	v_lshl_add_u64 v[138:139], s[10:11], 0, v[134:135]
	s_add_i32 m0, s24, 0xc000
	ds_read_b128 v[188:191], v143
	ds_read_b128 v[196:199], v143 offset:2048
	ds_read_b128 v[204:207], v143 offset:4096
	ds_read_b128 v[212:215], v143 offset:6144
	ds_read_b128 v[192:195], v143 offset:1024
	ds_read_b128 v[200:203], v143 offset:3072
	ds_read_b128 v[208:211], v143 offset:5120
	ds_read_b128 v[216:219], v143 offset:7168
	global_load_lds_dwordx4 v[138:139], off
	v_lshl_add_u64 v[138:139], s[10:11], 0, v[136:137]
	s_add_i32 m0, s24, 0xe000
	s_nop 0
	global_load_lds_dwordx4 v[138:139], off
	s_waitcnt lgkmcnt(8)
	s_barrier
	s_setprio 1
	s_waitcnt lgkmcnt(7)
	v_mfma_f32_16x16x32_bf16 v[124:127], v[158:161], v[188:191], 0
	v_mfma_f32_16x16x32_bf16 v[120:123], v[166:169], v[188:191], 0
	s_waitcnt lgkmcnt(6)
	v_mfma_f32_16x16x32_bf16 v[108:111], v[158:161], v[196:199], 0
	v_mfma_f32_16x16x32_bf16 v[104:107], v[166:169], v[196:199], 0
	s_waitcnt lgkmcnt(5)
	v_mfma_f32_16x16x32_bf16 v[92:95], v[158:161], v[204:207], 0
	v_mfma_f32_16x16x32_bf16 v[88:91], v[166:169], v[204:207], 0
	s_waitcnt lgkmcnt(4)
	v_mfma_f32_16x16x32_bf16 v[76:79], v[158:161], v[212:215], 0
	v_mfma_f32_16x16x32_bf16 v[72:75], v[166:169], v[212:215], 0
	s_waitcnt lgkmcnt(3)
	v_mfma_f32_16x16x32_bf16 v[124:127], v[162:165], v[192:195], v[124:127]
	v_mfma_f32_16x16x32_bf16 v[120:123], v[170:173], v[192:195], v[120:123]
	s_waitcnt lgkmcnt(2)
	v_mfma_f32_16x16x32_bf16 v[108:111], v[162:165], v[200:203], v[108:111]
	v_mfma_f32_16x16x32_bf16 v[104:107], v[170:173], v[200:203], v[104:107]
	s_waitcnt lgkmcnt(1)
	v_mfma_f32_16x16x32_bf16 v[92:95], v[162:165], v[208:211], v[92:95]
	v_mfma_f32_16x16x32_bf16 v[88:91], v[170:173], v[208:211], v[88:91]
	s_waitcnt lgkmcnt(0)
	v_mfma_f32_16x16x32_bf16 v[76:79], v[162:165], v[216:219], v[76:79]
	v_mfma_f32_16x16x32_bf16 v[72:75], v[170:173], v[216:219], v[72:75]
	s_setprio 0
	s_barrier
	s_add_i32 s78, 0, 0x14000
	v_add_u32_e32 v138, s78, v141
	s_add_i32 s73, s73, s23
	ds_read_b128 v[220:223], v138
	ds_read_b128 v[224:227], v138 offset:1024
	ds_read_b128 v[228:231], v138 offset:2048
	ds_read_b128 v[232:235], v138 offset:3072
	v_lshl_add_u64 v[138:139], s[14:15], 0, v[148:149]
	s_mov_b32 m0, s73
	v_lshl_add_u64 v[174:175], s[14:15], 0, v[128:129]
	global_load_lds_dwordx4 v[138:139], off
	s_add_i32 m0, s73, 0x2000
	s_nop 0
	global_load_lds_dwordx4 v[174:175], off
	s_barrier
	s_setprio 1
	s_waitcnt lgkmcnt(3)
	v_mfma_f32_16x16x32_bf16 v[116:119], v[220:223], v[188:191], 0
	s_waitcnt lgkmcnt(1)
	v_mfma_f32_16x16x32_bf16 v[112:115], v[228:231], v[188:191], 0
	v_mfma_f32_16x16x32_bf16 v[100:103], v[220:223], v[196:199], 0
	v_mfma_f32_16x16x32_bf16 v[96:99], v[228:231], v[196:199], 0
	v_mfma_f32_16x16x32_bf16 v[84:87], v[220:223], v[204:207], 0
	v_mfma_f32_16x16x32_bf16 v[80:83], v[228:231], v[204:207], 0
	v_mfma_f32_16x16x32_bf16 v[68:71], v[220:223], v[212:215], 0
	v_mfma_f32_16x16x32_bf16 v[64:67], v[228:231], v[212:215], 0
	v_mfma_f32_16x16x32_bf16 v[116:119], v[224:227], v[192:195], v[116:119]
	s_waitcnt lgkmcnt(0)
	v_mfma_f32_16x16x32_bf16 v[112:115], v[232:235], v[192:195], v[112:115]
	v_mfma_f32_16x16x32_bf16 v[100:103], v[224:227], v[200:203], v[100:103]
	v_mfma_f32_16x16x32_bf16 v[96:99], v[232:235], v[200:203], v[96:99]
	v_mfma_f32_16x16x32_bf16 v[84:87], v[224:227], v[208:211], v[84:87]
	v_mfma_f32_16x16x32_bf16 v[80:83], v[232:235], v[208:211], v[80:83]
	v_mfma_f32_16x16x32_bf16 v[68:71], v[224:227], v[216:219], v[68:71]
	v_mfma_f32_16x16x32_bf16 v[64:67], v[232:235], v[216:219], v[64:67]
	s_setprio 0
	s_mov_b32 m0, s24
	v_lshl_add_u64 v[236:237], s[20:21], 0, v[132:133]
	s_barrier
	ds_read_b128 v[188:191], v143 offset:16384
	ds_read_b128 v[196:199], v143 offset:18432
	ds_read_b128 v[204:207], v143 offset:20480
	ds_read_b128 v[212:215], v143 offset:22528
	ds_read_b128 v[192:195], v143 offset:17408
	ds_read_b128 v[200:203], v143 offset:19456
	ds_read_b128 v[208:211], v143 offset:21504
	ds_read_b128 v[216:219], v143 offset:23552
	global_load_lds_dwordx4 v[236:237], off
	v_lshl_add_u64 v[238:239], s[20:21], 0, v[130:131]
	s_mov_b32 m0, s25
	s_nop 0
	global_load_lds_dwordx4 v[238:239], off
	s_barrier
	s_setprio 1
	s_waitcnt lgkmcnt(7)
	v_mfma_f32_16x16x32_bf16 v[60:63], v[158:161], v[188:191], 0
	v_mfma_f32_16x16x32_bf16 v[56:59], v[166:169], v[188:191], 0
	s_waitcnt lgkmcnt(6)
	v_mfma_f32_16x16x32_bf16 v[44:47], v[158:161], v[196:199], 0
	v_mfma_f32_16x16x32_bf16 v[40:43], v[166:169], v[196:199], 0
	s_waitcnt lgkmcnt(5)
	v_mfma_f32_16x16x32_bf16 v[28:31], v[158:161], v[204:207], 0
	v_mfma_f32_16x16x32_bf16 v[24:27], v[166:169], v[204:207], 0
	s_waitcnt lgkmcnt(4)
	v_mfma_f32_16x16x32_bf16 v[12:15], v[158:161], v[212:215], 0
	v_mfma_f32_16x16x32_bf16 v[8:11], v[166:169], v[212:215], 0
	s_waitcnt lgkmcnt(3)
	v_mfma_f32_16x16x32_bf16 v[60:63], v[162:165], v[192:195], v[60:63]
	v_mfma_f32_16x16x32_bf16 v[56:59], v[170:173], v[192:195], v[56:59]
	s_waitcnt lgkmcnt(2)
	v_mfma_f32_16x16x32_bf16 v[44:47], v[162:165], v[200:203], v[44:47]
	v_mfma_f32_16x16x32_bf16 v[40:43], v[170:173], v[200:203], v[40:43]
	s_waitcnt lgkmcnt(1)
	v_mfma_f32_16x16x32_bf16 v[28:31], v[162:165], v[208:211], v[28:31]
	v_mfma_f32_16x16x32_bf16 v[24:27], v[170:173], v[208:211], v[24:27]
	s_waitcnt lgkmcnt(0)
	v_mfma_f32_16x16x32_bf16 v[12:15], v[162:165], v[216:219], v[12:15]
	v_mfma_f32_16x16x32_bf16 v[8:11], v[170:173], v[216:219], v[8:11]
	s_setprio 0
	s_barrier
	s_add_u32 s74, s14, 0x40000
	s_addc_u32 s75, s15, 0
	s_add_i32 s73, s78, s23
	v_lshl_add_u64 v[158:159], s[74:75], 0, v[148:149]
	s_mov_b32 m0, s73
	s_nop 0
	global_load_lds_dwordx4 v[158:159], off
	v_lshl_add_u64 v[158:159], s[74:75], 0, v[128:129]
	s_add_i32 m0, s73, 0x2000
	s_nop 0
	global_load_lds_dwordx4 v[158:159], off
	s_waitcnt vmcnt(6)
	s_barrier
	s_setprio 1
	v_mfma_f32_16x16x32_bf16 v[52:55], v[220:223], v[188:191], 0
	v_mfma_f32_16x16x32_bf16 v[48:51], v[228:231], v[188:191], 0
	v_mfma_f32_16x16x32_bf16 v[36:39], v[220:223], v[196:199], 0
	v_mfma_f32_16x16x32_bf16 v[32:35], v[228:231], v[196:199], 0
	v_mfma_f32_16x16x32_bf16 v[20:23], v[220:223], v[204:207], 0
	v_mfma_f32_16x16x32_bf16 v[16:19], v[228:231], v[204:207], 0
	v_mfma_f32_16x16x32_bf16 v[4:7], v[220:223], v[212:215], 0
	v_mfma_f32_16x16x32_bf16 v[0:3], v[228:231], v[212:215], 0
	v_mfma_f32_16x16x32_bf16 v[52:55], v[224:227], v[192:195], v[52:55]
	v_mfma_f32_16x16x32_bf16 v[48:51], v[232:235], v[192:195], v[48:51]
	v_mfma_f32_16x16x32_bf16 v[36:39], v[224:227], v[200:203], v[36:39]
	v_mfma_f32_16x16x32_bf16 v[32:35], v[232:235], v[200:203], v[32:35]
	v_mfma_f32_16x16x32_bf16 v[20:23], v[224:227], v[208:211], v[20:23]
	v_mfma_f32_16x16x32_bf16 v[16:19], v[232:235], v[208:211], v[16:19]
	v_mfma_f32_16x16x32_bf16 v[4:7], v[224:227], v[216:219], v[4:7]
	v_mfma_f32_16x16x32_bf16 v[0:3], v[232:235], v[216:219], v[0:3]
	s_setprio 0
	s_add_i32 s73, 0, 0x18000
	v_add_u32_e32 v170, s73, v141
	s_barrier
	ds_read_b128 v[158:161], v170
	ds_read_b128 v[162:165], v170 offset:1024
	ds_read_b128 v[166:169], v170 offset:2048
	ds_read_b128 v[170:173], v170 offset:3072
	s_add_u32 s20, s20, 0x40000
	s_addc_u32 s21, s21, 0
	s_mov_b32 m0, s36
	v_lshl_add_u64 v[220:221], s[20:21], 0, v[132:133]
	ds_read_b128 v[188:191], v143 offset:32768
	ds_read_b128 v[196:199], v143 offset:34816
	ds_read_b128 v[204:207], v143 offset:36864
	ds_read_b128 v[212:215], v143 offset:38912
	ds_read_b128 v[192:195], v143 offset:33792
	ds_read_b128 v[200:203], v143 offset:35840
	ds_read_b128 v[208:211], v143 offset:37888
	ds_read_b128 v[216:219], v143 offset:39936
	global_load_lds_dwordx4 v[220:221], off
	v_lshl_add_u64 v[220:221], s[20:21], 0, v[130:131]
	s_mov_b32 m0, s37
	s_nop 0
	global_load_lds_dwordx4 v[220:221], off
	s_waitcnt lgkmcnt(8)
	s_barrier
	s_setprio 1
	s_waitcnt lgkmcnt(7)
	v_mfma_f32_16x16x32_bf16 v[124:127], v[158:161], v[188:191], v[124:127]
	v_mfma_f32_16x16x32_bf16 v[120:123], v[166:169], v[188:191], v[120:123]
	s_waitcnt lgkmcnt(6)
	v_mfma_f32_16x16x32_bf16 v[108:111], v[158:161], v[196:199], v[108:111]
	v_mfma_f32_16x16x32_bf16 v[104:107], v[166:169], v[196:199], v[104:107]
	s_waitcnt lgkmcnt(5)
	v_mfma_f32_16x16x32_bf16 v[92:95], v[158:161], v[204:207], v[92:95]
	v_mfma_f32_16x16x32_bf16 v[88:91], v[166:169], v[204:207], v[88:91]
	s_waitcnt lgkmcnt(4)
	v_mfma_f32_16x16x32_bf16 v[76:79], v[158:161], v[212:215], v[76:79]
	v_mfma_f32_16x16x32_bf16 v[72:75], v[166:169], v[212:215], v[72:75]
	s_waitcnt lgkmcnt(3)
	v_mfma_f32_16x16x32_bf16 v[124:127], v[162:165], v[192:195], v[124:127]
	v_mfma_f32_16x16x32_bf16 v[120:123], v[170:173], v[192:195], v[120:123]
	s_waitcnt lgkmcnt(2)
	v_mfma_f32_16x16x32_bf16 v[108:111], v[162:165], v[200:203], v[108:111]
	v_mfma_f32_16x16x32_bf16 v[104:107], v[170:173], v[200:203], v[104:107]
	s_waitcnt lgkmcnt(1)
	v_mfma_f32_16x16x32_bf16 v[92:95], v[162:165], v[208:211], v[92:95]
	v_mfma_f32_16x16x32_bf16 v[88:91], v[170:173], v[208:211], v[88:91]
	s_waitcnt lgkmcnt(0)
	v_mfma_f32_16x16x32_bf16 v[76:79], v[162:165], v[216:219], v[76:79]
	v_mfma_f32_16x16x32_bf16 v[72:75], v[170:173], v[216:219], v[72:75]
	s_setprio 0
	s_barrier
	s_add_i32 s20, 0, 0x1c000
	s_add_i32 s21, s73, s23
	v_add_u32_e32 v232, s20, v141
	v_lshl_add_u64 v[138:139], v[138:139], 0, s[28:29]
	s_mov_b32 m0, s21
	ds_read_b128 v[220:223], v232
	ds_read_b128 v[224:227], v232 offset:1024
	ds_read_b128 v[228:231], v232 offset:2048
	ds_read_b128 v[232:235], v232 offset:3072
	global_load_lds_dwordx4 v[138:139], off
	v_lshl_add_u64 v[138:139], v[174:175], 0, s[28:29]
	s_add_i32 m0, s21, 0x2000
	s_nop 0
	global_load_lds_dwordx4 v[138:139], off
	s_barrier
	s_setprio 1
	s_waitcnt lgkmcnt(3)
	v_mfma_f32_16x16x32_bf16 v[116:119], v[220:223], v[188:191], v[116:119]
	s_waitcnt lgkmcnt(1)
	v_mfma_f32_16x16x32_bf16 v[112:115], v[228:231], v[188:191], v[112:115]
	v_mfma_f32_16x16x32_bf16 v[100:103], v[220:223], v[196:199], v[100:103]
	v_mfma_f32_16x16x32_bf16 v[96:99], v[228:231], v[196:199], v[96:99]
	v_mfma_f32_16x16x32_bf16 v[84:87], v[220:223], v[204:207], v[84:87]
	v_mfma_f32_16x16x32_bf16 v[80:83], v[228:231], v[204:207], v[80:83]
	v_mfma_f32_16x16x32_bf16 v[68:71], v[220:223], v[212:215], v[68:71]
	v_mfma_f32_16x16x32_bf16 v[64:67], v[228:231], v[212:215], v[64:67]
	v_mfma_f32_16x16x32_bf16 v[116:119], v[224:227], v[192:195], v[116:119]
	s_waitcnt lgkmcnt(0)
	v_mfma_f32_16x16x32_bf16 v[112:115], v[232:235], v[192:195], v[112:115]
	v_mfma_f32_16x16x32_bf16 v[100:103], v[224:227], v[200:203], v[100:103]
	v_mfma_f32_16x16x32_bf16 v[96:99], v[232:235], v[200:203], v[96:99]
	v_mfma_f32_16x16x32_bf16 v[84:87], v[224:227], v[208:211], v[84:87]
	v_mfma_f32_16x16x32_bf16 v[80:83], v[232:235], v[208:211], v[80:83]
	v_mfma_f32_16x16x32_bf16 v[68:71], v[224:227], v[216:219], v[68:71]
	v_mfma_f32_16x16x32_bf16 v[64:67], v[232:235], v[216:219], v[64:67]
	s_setprio 0
	s_mov_b32 m0, s38
	v_lshl_add_u64 v[138:139], v[236:237], 0, s[28:29]
	s_barrier
	ds_read_b128 v[188:191], v143 offset:49152
	ds_read_b128 v[196:199], v143 offset:51200
	ds_read_b128 v[204:207], v143 offset:53248
	ds_read_b128 v[212:215], v143 offset:55296
	ds_read_b128 v[192:195], v143 offset:50176
	ds_read_b128 v[200:203], v143 offset:52224
	ds_read_b128 v[208:211], v143 offset:54272
	ds_read_b128 v[216:219], v143 offset:56320
	global_load_lds_dwordx4 v[138:139], off
	v_lshl_add_u64 v[138:139], v[238:239], 0, s[28:29]
	s_mov_b32 m0, s39
	s_nop 0
	global_load_lds_dwordx4 v[138:139], off
	s_barrier
	s_setprio 1
	s_waitcnt lgkmcnt(7)
	v_mfma_f32_16x16x32_bf16 v[60:63], v[158:161], v[188:191], v[60:63]
	v_mfma_f32_16x16x32_bf16 v[56:59], v[166:169], v[188:191], v[56:59]
	s_waitcnt lgkmcnt(6)
	v_mfma_f32_16x16x32_bf16 v[44:47], v[158:161], v[196:199], v[44:47]
	v_mfma_f32_16x16x32_bf16 v[40:43], v[166:169], v[196:199], v[40:43]
	s_waitcnt lgkmcnt(5)
	v_mfma_f32_16x16x32_bf16 v[28:31], v[158:161], v[204:207], v[28:31]
	v_mfma_f32_16x16x32_bf16 v[24:27], v[166:169], v[204:207], v[24:27]
	s_waitcnt lgkmcnt(4)
	v_mfma_f32_16x16x32_bf16 v[12:15], v[158:161], v[212:215], v[12:15]
	v_mfma_f32_16x16x32_bf16 v[8:11], v[166:169], v[212:215], v[8:11]
	s_waitcnt lgkmcnt(3)
	v_mfma_f32_16x16x32_bf16 v[60:63], v[162:165], v[192:195], v[60:63]
	v_mfma_f32_16x16x32_bf16 v[56:59], v[170:173], v[192:195], v[56:59]
	s_waitcnt lgkmcnt(2)
	v_mfma_f32_16x16x32_bf16 v[44:47], v[162:165], v[200:203], v[44:47]
	v_mfma_f32_16x16x32_bf16 v[40:43], v[170:173], v[200:203], v[40:43]
	s_waitcnt lgkmcnt(1)
	v_mfma_f32_16x16x32_bf16 v[28:31], v[162:165], v[208:211], v[28:31]
	v_mfma_f32_16x16x32_bf16 v[24:27], v[170:173], v[208:211], v[24:27]
	s_waitcnt lgkmcnt(0)
	v_mfma_f32_16x16x32_bf16 v[12:15], v[162:165], v[216:219], v[12:15]
	v_mfma_f32_16x16x32_bf16 v[8:11], v[170:173], v[216:219], v[8:11]
	s_setprio 0
	s_barrier
	s_add_u32 s14, s14, 0x40080
	s_addc_u32 s15, s15, 0
	s_add_i32 s20, s20, s23
	v_lshl_add_u64 v[138:139], s[14:15], 0, v[148:149]
	s_mov_b32 m0, s20
	s_nop 0
	global_load_lds_dwordx4 v[138:139], off
	v_lshl_add_u64 v[138:139], s[14:15], 0, v[128:129]
	s_add_i32 m0, s20, 0x2000
	s_nop 0
	global_load_lds_dwordx4 v[138:139], off
	s_waitcnt vmcnt(6)
	s_barrier
	s_setprio 1
	v_mfma_f32_16x16x32_bf16 v[52:55], v[220:223], v[188:191], v[52:55]
	v_mfma_f32_16x16x32_bf16 v[48:51], v[228:231], v[188:191], v[48:51]
	v_mfma_f32_16x16x32_bf16 v[36:39], v[220:223], v[196:199], v[36:39]
	v_mfma_f32_16x16x32_bf16 v[32:35], v[228:231], v[196:199], v[32:35]
	v_mfma_f32_16x16x32_bf16 v[20:23], v[220:223], v[204:207], v[20:23]
	v_mfma_f32_16x16x32_bf16 v[16:19], v[228:231], v[204:207], v[16:19]
	v_mfma_f32_16x16x32_bf16 v[4:7], v[220:223], v[212:215], v[4:7]
	v_mfma_f32_16x16x32_bf16 v[0:3], v[228:231], v[212:215], v[0:3]
	v_mfma_f32_16x16x32_bf16 v[52:55], v[224:227], v[192:195], v[52:55]
	v_mfma_f32_16x16x32_bf16 v[48:51], v[232:235], v[192:195], v[48:51]
	v_mfma_f32_16x16x32_bf16 v[36:39], v[224:227], v[200:203], v[36:39]
	v_mfma_f32_16x16x32_bf16 v[32:35], v[232:235], v[200:203], v[32:35]
	v_mfma_f32_16x16x32_bf16 v[20:23], v[224:227], v[208:211], v[20:23]
	v_mfma_f32_16x16x32_bf16 v[16:19], v[232:235], v[208:211], v[16:19]
	v_mfma_f32_16x16x32_bf16 v[4:7], v[224:227], v[216:219], v[4:7]
	v_mfma_f32_16x16x32_bf16 v[0:3], v[232:235], v[216:219], v[0:3]
	s_setprio 0
	s_add_i32 s51, s51, 2
	s_add_u32 s10, s10, 0x100
	s_addc_u32 s11, s11, 0
	s_add_u32 s47, s47, 0x100
	s_addc_u32 s50, s50, 0
	s_cmp_gt_u32 s51, 13
	s_barrier
	s_cbranch_scc1 .Lpeel_after_g1
.LBB0_705:
	s_add_u32 s14, s10, 0xfffc0080
	s_addc_u32 s15, s11, -1
	s_add_i32 s73, 0, 0x10000
	v_add_u32_e32 v138, s73, v141
	ds_read_b128 v[158:161], v138
	ds_read_b128 v[162:165], v138 offset:1024
	ds_read_b128 v[166:169], v138 offset:2048
	ds_read_b128 v[170:173], v138 offset:3072
	s_cmp_eq_u32 s51, 12
	s_cselect_b32 s21, s3, s15
	s_cselect_b32 s20, s45, s14
	s_cselect_b32 s15, s1, s50
	s_cselect_b32 s14, s46, s47
	v_lshl_add_u64 v[138:139], s[10:11], 0, v[134:135]
	s_add_i32 m0, s24, 0xc000
	ds_read_b128 v[188:191], v143
	ds_read_b128 v[196:199], v143 offset:2048
	ds_read_b128 v[204:207], v143 offset:4096
	ds_read_b128 v[212:215], v143 offset:6144
	ds_read_b128 v[192:195], v143 offset:1024
	ds_read_b128 v[200:203], v143 offset:3072
	ds_read_b128 v[208:211], v143 offset:5120
	ds_read_b128 v[216:219], v143 offset:7168
	global_load_lds_dwordx4 v[138:139], off
	v_lshl_add_u64 v[138:139], s[10:11], 0, v[136:137]
	s_add_i32 m0, s24, 0xe000
	s_nop 0
	global_load_lds_dwordx4 v[138:139], off
	s_waitcnt lgkmcnt(8)
	s_barrier
	s_setprio 1
	s_waitcnt lgkmcnt(7)
	v_mfma_f32_16x16x32_bf16 v[124:127], v[158:161], v[188:191], v[124:127]
	v_mfma_f32_16x16x32_bf16 v[120:123], v[166:169], v[188:191], v[120:123]
	s_waitcnt lgkmcnt(6)
	v_mfma_f32_16x16x32_bf16 v[108:111], v[158:161], v[196:199], v[108:111]
	v_mfma_f32_16x16x32_bf16 v[104:107], v[166:169], v[196:199], v[104:107]
	s_waitcnt lgkmcnt(5)
	v_mfma_f32_16x16x32_bf16 v[92:95], v[158:161], v[204:207], v[92:95]
	v_mfma_f32_16x16x32_bf16 v[88:91], v[166:169], v[204:207], v[88:91]
	s_waitcnt lgkmcnt(4)
	v_mfma_f32_16x16x32_bf16 v[76:79], v[158:161], v[212:215], v[76:79]
	v_mfma_f32_16x16x32_bf16 v[72:75], v[166:169], v[212:215], v[72:75]
	s_waitcnt lgkmcnt(3)
	v_mfma_f32_16x16x32_bf16 v[124:127], v[162:165], v[192:195], v[124:127]
	v_mfma_f32_16x16x32_bf16 v[120:123], v[170:173], v[192:195], v[120:123]
	s_waitcnt lgkmcnt(2)
	v_mfma_f32_16x16x32_bf16 v[108:111], v[162:165], v[200:203], v[108:111]
	v_mfma_f32_16x16x32_bf16 v[104:107], v[170:173], v[200:203], v[104:107]
	s_waitcnt lgkmcnt(1)
	v_mfma_f32_16x16x32_bf16 v[92:95], v[162:165], v[208:211], v[92:95]
	v_mfma_f32_16x16x32_bf16 v[88:91], v[170:173], v[208:211], v[88:91]
	s_waitcnt lgkmcnt(0)
	v_mfma_f32_16x16x32_bf16 v[76:79], v[162:165], v[216:219], v[76:79]
	v_mfma_f32_16x16x32_bf16 v[72:75], v[170:173], v[216:219], v[72:75]
	s_setprio 0
	s_barrier
	s_add_i32 s78, 0, 0x14000
	v_add_u32_e32 v138, s78, v141
	s_add_i32 s73, s73, s23
	ds_read_b128 v[220:223], v138
	ds_read_b128 v[224:227], v138 offset:1024
	ds_read_b128 v[228:231], v138 offset:2048
	ds_read_b128 v[232:235], v138 offset:3072
	v_lshl_add_u64 v[138:139], s[14:15], 0, v[148:149]
	s_mov_b32 m0, s73
	v_lshl_add_u64 v[174:175], s[14:15], 0, v[128:129]
	global_load_lds_dwordx4 v[138:139], off
	s_add_i32 m0, s73, 0x2000
	s_nop 0
	global_load_lds_dwordx4 v[174:175], off
	s_barrier
	s_setprio 1
	s_waitcnt lgkmcnt(3)
	v_mfma_f32_16x16x32_bf16 v[116:119], v[220:223], v[188:191], v[116:119]
	s_waitcnt lgkmcnt(1)
	v_mfma_f32_16x16x32_bf16 v[112:115], v[228:231], v[188:191], v[112:115]
	v_mfma_f32_16x16x32_bf16 v[100:103], v[220:223], v[196:199], v[100:103]
	v_mfma_f32_16x16x32_bf16 v[96:99], v[228:231], v[196:199], v[96:99]
	v_mfma_f32_16x16x32_bf16 v[84:87], v[220:223], v[204:207], v[84:87]
	v_mfma_f32_16x16x32_bf16 v[80:83], v[228:231], v[204:207], v[80:83]
	v_mfma_f32_16x16x32_bf16 v[68:71], v[220:223], v[212:215], v[68:71]
	v_mfma_f32_16x16x32_bf16 v[64:67], v[228:231], v[212:215], v[64:67]
	v_mfma_f32_16x16x32_bf16 v[116:119], v[224:227], v[192:195], v[116:119]
	s_waitcnt lgkmcnt(0)
	v_mfma_f32_16x16x32_bf16 v[112:115], v[232:235], v[192:195], v[112:115]
	v_mfma_f32_16x16x32_bf16 v[100:103], v[224:227], v[200:203], v[100:103]
	v_mfma_f32_16x16x32_bf16 v[96:99], v[232:235], v[200:203], v[96:99]
	v_mfma_f32_16x16x32_bf16 v[84:87], v[224:227], v[208:211], v[84:87]
	v_mfma_f32_16x16x32_bf16 v[80:83], v[232:235], v[208:211], v[80:83]
	v_mfma_f32_16x16x32_bf16 v[68:71], v[224:227], v[216:219], v[68:71]
	v_mfma_f32_16x16x32_bf16 v[64:67], v[232:235], v[216:219], v[64:67]
	s_setprio 0
	s_mov_b32 m0, s24
	v_lshl_add_u64 v[236:237], s[20:21], 0, v[132:133]
	s_barrier
	ds_read_b128 v[188:191], v143 offset:16384
	ds_read_b128 v[196:199], v143 offset:18432
	ds_read_b128 v[204:207], v143 offset:20480
	ds_read_b128 v[212:215], v143 offset:22528
	ds_read_b128 v[192:195], v143 offset:17408
	ds_read_b128 v[200:203], v143 offset:19456
	ds_read_b128 v[208:211], v143 offset:21504
	ds_read_b128 v[216:219], v143 offset:23552
	global_load_lds_dwordx4 v[236:237], off
	v_lshl_add_u64 v[238:239], s[20:21], 0, v[130:131]
	s_mov_b32 m0, s25
	s_nop 0
	global_load_lds_dwordx4 v[238:239], off
	s_barrier
	s_setprio 1
	s_waitcnt lgkmcnt(7)
	v_mfma_f32_16x16x32_bf16 v[60:63], v[158:161], v[188:191], v[60:63]
	v_mfma_f32_16x16x32_bf16 v[56:59], v[166:169], v[188:191], v[56:59]
	s_waitcnt lgkmcnt(6)
	v_mfma_f32_16x16x32_bf16 v[44:47], v[158:161], v[196:199], v[44:47]
	v_mfma_f32_16x16x32_bf16 v[40:43], v[166:169], v[196:199], v[40:43]
	s_waitcnt lgkmcnt(5)
	v_mfma_f32_16x16x32_bf16 v[28:31], v[158:161], v[204:207], v[28:31]
	v_mfma_f32_16x16x32_bf16 v[24:27], v[166:169], v[204:207], v[24:27]
	s_waitcnt lgkmcnt(4)
	v_mfma_f32_16x16x32_bf16 v[12:15], v[158:161], v[212:215], v[12:15]
	v_mfma_f32_16x16x32_bf16 v[8:11], v[166:169], v[212:215], v[8:11]
	s_waitcnt lgkmcnt(3)
	v_mfma_f32_16x16x32_bf16 v[60:63], v[162:165], v[192:195], v[60:63]
	v_mfma_f32_16x16x32_bf16 v[56:59], v[170:173], v[192:195], v[56:59]
	s_waitcnt lgkmcnt(2)
	v_mfma_f32_16x16x32_bf16 v[44:47], v[162:165], v[200:203], v[44:47]
	v_mfma_f32_16x16x32_bf16 v[40:43], v[170:173], v[200:203], v[40:43]
	s_waitcnt lgkmcnt(1)
	v_mfma_f32_16x16x32_bf16 v[28:31], v[162:165], v[208:211], v[28:31]
	v_mfma_f32_16x16x32_bf16 v[24:27], v[170:173], v[208:211], v[24:27]
	s_waitcnt lgkmcnt(0)
	v_mfma_f32_16x16x32_bf16 v[12:15], v[162:165], v[216:219], v[12:15]
	v_mfma_f32_16x16x32_bf16 v[8:11], v[170:173], v[216:219], v[8:11]
	s_setprio 0
	s_barrier
	s_add_u32 s74, s14, 0x40000
	s_addc_u32 s75, s15, 0
	s_add_i32 s73, s78, s23
	v_lshl_add_u64 v[158:159], s[74:75], 0, v[148:149]
	s_mov_b32 m0, s73
	s_nop 0
	global_load_lds_dwordx4 v[158:159], off
	v_lshl_add_u64 v[158:159], s[74:75], 0, v[128:129]
	s_add_i32 m0, s73, 0x2000
	s_nop 0
	global_load_lds_dwordx4 v[158:159], off
	s_waitcnt vmcnt(6)
	s_barrier
	s_setprio 1
	v_mfma_f32_16x16x32_bf16 v[52:55], v[220:223], v[188:191], v[52:55]
	v_mfma_f32_16x16x32_bf16 v[48:51], v[228:231], v[188:191], v[48:51]
	v_mfma_f32_16x16x32_bf16 v[36:39], v[220:223], v[196:199], v[36:39]
	v_mfma_f32_16x16x32_bf16 v[32:35], v[228:231], v[196:199], v[32:35]
	v_mfma_f32_16x16x32_bf16 v[20:23], v[220:223], v[204:207], v[20:23]
	v_mfma_f32_16x16x32_bf16 v[16:19], v[228:231], v[204:207], v[16:19]
	v_mfma_f32_16x16x32_bf16 v[4:7], v[220:223], v[212:215], v[4:7]
	v_mfma_f32_16x16x32_bf16 v[0:3], v[228:231], v[212:215], v[0:3]
	v_mfma_f32_16x16x32_bf16 v[52:55], v[224:227], v[192:195], v[52:55]
	v_mfma_f32_16x16x32_bf16 v[48:51], v[232:235], v[192:195], v[48:51]
	v_mfma_f32_16x16x32_bf16 v[36:39], v[224:227], v[200:203], v[36:39]
	v_mfma_f32_16x16x32_bf16 v[32:35], v[232:235], v[200:203], v[32:35]
	v_mfma_f32_16x16x32_bf16 v[20:23], v[224:227], v[208:211], v[20:23]
	v_mfma_f32_16x16x32_bf16 v[16:19], v[232:235], v[208:211], v[16:19]
	v_mfma_f32_16x16x32_bf16 v[4:7], v[224:227], v[216:219], v[4:7]
	v_mfma_f32_16x16x32_bf16 v[0:3], v[232:235], v[216:219], v[0:3]
	s_setprio 0
	s_add_i32 s73, 0, 0x18000
	v_add_u32_e32 v170, s73, v141
	s_barrier
	ds_read_b128 v[158:161], v170
	ds_read_b128 v[162:165], v170 offset:1024
	ds_read_b128 v[166:169], v170 offset:2048
	ds_read_b128 v[170:173], v170 offset:3072
	s_add_u32 s20, s20, 0x40000
	s_addc_u32 s21, s21, 0
	s_mov_b32 m0, s36
	v_lshl_add_u64 v[220:221], s[20:21], 0, v[132:133]
	ds_read_b128 v[188:191], v143 offset:32768
	ds_read_b128 v[196:199], v143 offset:34816
	ds_read_b128 v[204:207], v143 offset:36864
	ds_read_b128 v[212:215], v143 offset:38912
	ds_read_b128 v[192:195], v143 offset:33792
	ds_read_b128 v[200:203], v143 offset:35840
	ds_read_b128 v[208:211], v143 offset:37888
	ds_read_b128 v[216:219], v143 offset:39936
	global_load_lds_dwordx4 v[220:221], off
	v_lshl_add_u64 v[220:221], s[20:21], 0, v[130:131]
	s_mov_b32 m0, s37
	s_nop 0
	global_load_lds_dwordx4 v[220:221], off
	s_waitcnt lgkmcnt(8)
	s_barrier
	s_setprio 1
	s_waitcnt lgkmcnt(7)
	v_mfma_f32_16x16x32_bf16 v[124:127], v[158:161], v[188:191], v[124:127]
	v_mfma_f32_16x16x32_bf16 v[120:123], v[166:169], v[188:191], v[120:123]
	s_waitcnt lgkmcnt(6)
	v_mfma_f32_16x16x32_bf16 v[108:111], v[158:161], v[196:199], v[108:111]
	v_mfma_f32_16x16x32_bf16 v[104:107], v[166:169], v[196:199], v[104:107]
	s_waitcnt lgkmcnt(5)
	v_mfma_f32_16x16x32_bf16 v[92:95], v[158:161], v[204:207], v[92:95]
	v_mfma_f32_16x16x32_bf16 v[88:91], v[166:169], v[204:207], v[88:91]
	s_waitcnt lgkmcnt(4)
	v_mfma_f32_16x16x32_bf16 v[76:79], v[158:161], v[212:215], v[76:79]
	v_mfma_f32_16x16x32_bf16 v[72:75], v[166:169], v[212:215], v[72:75]
	s_waitcnt lgkmcnt(3)
	v_mfma_f32_16x16x32_bf16 v[124:127], v[162:165], v[192:195], v[124:127]
	v_mfma_f32_16x16x32_bf16 v[120:123], v[170:173], v[192:195], v[120:123]
	s_waitcnt lgkmcnt(2)
	v_mfma_f32_16x16x32_bf16 v[108:111], v[162:165], v[200:203], v[108:111]
	v_mfma_f32_16x16x32_bf16 v[104:107], v[170:173], v[200:203], v[104:107]
	s_waitcnt lgkmcnt(1)
	v_mfma_f32_16x16x32_bf16 v[92:95], v[162:165], v[208:211], v[92:95]
	v_mfma_f32_16x16x32_bf16 v[88:91], v[170:173], v[208:211], v[88:91]
	s_waitcnt lgkmcnt(0)
	v_mfma_f32_16x16x32_bf16 v[76:79], v[162:165], v[216:219], v[76:79]
	v_mfma_f32_16x16x32_bf16 v[72:75], v[170:173], v[216:219], v[72:75]
	s_setprio 0
	s_barrier
	s_add_i32 s20, 0, 0x1c000
	s_add_i32 s21, s73, s23
	v_add_u32_e32 v232, s20, v141
	v_lshl_add_u64 v[138:139], v[138:139], 0, s[28:29]
	s_mov_b32 m0, s21
	ds_read_b128 v[220:223], v232
	ds_read_b128 v[224:227], v232 offset:1024
	ds_read_b128 v[228:231], v232 offset:2048
	ds_read_b128 v[232:235], v232 offset:3072
	global_load_lds_dwordx4 v[138:139], off
	v_lshl_add_u64 v[138:139], v[174:175], 0, s[28:29]
	s_add_i32 m0, s21, 0x2000
	s_nop 0
	global_load_lds_dwordx4 v[138:139], off
	s_barrier
	s_setprio 1
	s_waitcnt lgkmcnt(3)
	v_mfma_f32_16x16x32_bf16 v[116:119], v[220:223], v[188:191], v[116:119]
	s_waitcnt lgkmcnt(1)
	v_mfma_f32_16x16x32_bf16 v[112:115], v[228:231], v[188:191], v[112:115]
	v_mfma_f32_16x16x32_bf16 v[100:103], v[220:223], v[196:199], v[100:103]
	v_mfma_f32_16x16x32_bf16 v[96:99], v[228:231], v[196:199], v[96:99]
	v_mfma_f32_16x16x32_bf16 v[84:87], v[220:223], v[204:207], v[84:87]
	v_mfma_f32_16x16x32_bf16 v[80:83], v[228:231], v[204:207], v[80:83]
	v_mfma_f32_16x16x32_bf16 v[68:71], v[220:223], v[212:215], v[68:71]
	v_mfma_f32_16x16x32_bf16 v[64:67], v[228:231], v[212:215], v[64:67]
	v_mfma_f32_16x16x32_bf16 v[116:119], v[224:227], v[192:195], v[116:119]
	s_waitcnt lgkmcnt(0)
	v_mfma_f32_16x16x32_bf16 v[112:115], v[232:235], v[192:195], v[112:115]
	v_mfma_f32_16x16x32_bf16 v[100:103], v[224:227], v[200:203], v[100:103]
	v_mfma_f32_16x16x32_bf16 v[96:99], v[232:235], v[200:203], v[96:99]
	v_mfma_f32_16x16x32_bf16 v[84:87], v[224:227], v[208:211], v[84:87]
	v_mfma_f32_16x16x32_bf16 v[80:83], v[232:235], v[208:211], v[80:83]
	v_mfma_f32_16x16x32_bf16 v[68:71], v[224:227], v[216:219], v[68:71]
	v_mfma_f32_16x16x32_bf16 v[64:67], v[232:235], v[216:219], v[64:67]
	s_setprio 0
	s_mov_b32 m0, s38
	v_lshl_add_u64 v[138:139], v[236:237], 0, s[28:29]
	s_barrier
	ds_read_b128 v[188:191], v143 offset:49152
	ds_read_b128 v[196:199], v143 offset:51200
	ds_read_b128 v[204:207], v143 offset:53248
	ds_read_b128 v[212:215], v143 offset:55296
	ds_read_b128 v[192:195], v143 offset:50176
	ds_read_b128 v[200:203], v143 offset:52224
	ds_read_b128 v[208:211], v143 offset:54272
	ds_read_b128 v[216:219], v143 offset:56320
	global_load_lds_dwordx4 v[138:139], off
	v_lshl_add_u64 v[138:139], v[238:239], 0, s[28:29]
	s_mov_b32 m0, s39
	s_nop 0
	global_load_lds_dwordx4 v[138:139], off
	s_barrier
	s_setprio 1
	s_waitcnt lgkmcnt(7)
	v_mfma_f32_16x16x32_bf16 v[60:63], v[158:161], v[188:191], v[60:63]
	v_mfma_f32_16x16x32_bf16 v[56:59], v[166:169], v[188:191], v[56:59]
	s_waitcnt lgkmcnt(6)
	v_mfma_f32_16x16x32_bf16 v[44:47], v[158:161], v[196:199], v[44:47]
	v_mfma_f32_16x16x32_bf16 v[40:43], v[166:169], v[196:199], v[40:43]
	s_waitcnt lgkmcnt(5)
	v_mfma_f32_16x16x32_bf16 v[28:31], v[158:161], v[204:207], v[28:31]
	v_mfma_f32_16x16x32_bf16 v[24:27], v[166:169], v[204:207], v[24:27]
	s_waitcnt lgkmcnt(4)
	v_mfma_f32_16x16x32_bf16 v[12:15], v[158:161], v[212:215], v[12:15]
	v_mfma_f32_16x16x32_bf16 v[8:11], v[166:169], v[212:215], v[8:11]
	s_waitcnt lgkmcnt(3)
	v_mfma_f32_16x16x32_bf16 v[60:63], v[162:165], v[192:195], v[60:63]
	v_mfma_f32_16x16x32_bf16 v[56:59], v[170:173], v[192:195], v[56:59]
	s_waitcnt lgkmcnt(2)
	v_mfma_f32_16x16x32_bf16 v[44:47], v[162:165], v[200:203], v[44:47]
	v_mfma_f32_16x16x32_bf16 v[40:43], v[170:173], v[200:203], v[40:43]
	s_waitcnt lgkmcnt(1)
	v_mfma_f32_16x16x32_bf16 v[28:31], v[162:165], v[208:211], v[28:31]
	v_mfma_f32_16x16x32_bf16 v[24:27], v[170:173], v[208:211], v[24:27]
	s_waitcnt lgkmcnt(0)
	v_mfma_f32_16x16x32_bf16 v[12:15], v[162:165], v[216:219], v[12:15]
	v_mfma_f32_16x16x32_bf16 v[8:11], v[170:173], v[216:219], v[8:11]
	s_setprio 0
	s_barrier
	s_add_u32 s14, s14, 0x40080
	s_addc_u32 s15, s15, 0
	s_add_i32 s20, s20, s23
	v_lshl_add_u64 v[138:139], s[14:15], 0, v[148:149]
	s_mov_b32 m0, s20
	s_nop 0
	global_load_lds_dwordx4 v[138:139], off
	v_lshl_add_u64 v[138:139], s[14:15], 0, v[128:129]
	s_add_i32 m0, s20, 0x2000
	s_nop 0
	global_load_lds_dwordx4 v[138:139], off
	s_waitcnt vmcnt(6)
	s_barrier
	s_setprio 1
	v_mfma_f32_16x16x32_bf16 v[52:55], v[220:223], v[188:191], v[52:55]
	v_mfma_f32_16x16x32_bf16 v[48:51], v[228:231], v[188:191], v[48:51]
	v_mfma_f32_16x16x32_bf16 v[36:39], v[220:223], v[196:199], v[36:39]
	v_mfma_f32_16x16x32_bf16 v[32:35], v[228:231], v[196:199], v[32:35]
	v_mfma_f32_16x16x32_bf16 v[20:23], v[220:223], v[204:207], v[20:23]
	v_mfma_f32_16x16x32_bf16 v[16:19], v[228:231], v[204:207], v[16:19]
	v_mfma_f32_16x16x32_bf16 v[4:7], v[220:223], v[212:215], v[4:7]
	v_mfma_f32_16x16x32_bf16 v[0:3], v[228:231], v[212:215], v[0:3]
	v_mfma_f32_16x16x32_bf16 v[52:55], v[224:227], v[192:195], v[52:55]
	v_mfma_f32_16x16x32_bf16 v[48:51], v[232:235], v[192:195], v[48:51]
	v_mfma_f32_16x16x32_bf16 v[36:39], v[224:227], v[200:203], v[36:39]
	v_mfma_f32_16x16x32_bf16 v[32:35], v[232:235], v[200:203], v[32:35]
	v_mfma_f32_16x16x32_bf16 v[20:23], v[224:227], v[208:211], v[20:23]
	v_mfma_f32_16x16x32_bf16 v[16:19], v[232:235], v[208:211], v[16:19]
	v_mfma_f32_16x16x32_bf16 v[4:7], v[224:227], v[216:219], v[4:7]
	v_mfma_f32_16x16x32_bf16 v[0:3], v[232:235], v[216:219], v[0:3]
	s_setprio 0
	s_add_i32 s51, s51, 2
	s_add_u32 s10, s10, 0x100
	s_addc_u32 s11, s11, 0
	s_add_u32 s47, s47, 0x100
	s_addc_u32 s50, s50, 0
	s_cmp_gt_u32 s51, 13
	s_barrier
	s_cbranch_scc0 .LBB0_705
